# v5: v4 + the barrier closing each MFMA segment moved in front of its last 3 MFMAs (tail at raised priority) in 6 K-loops
# baseline (speedup 1.0000x reference)
; #define PG8_STAGE(bufoff, gbase, voff) do { _Pragma("unroll") for (int _i = 0; _i < 2; ++_i) \
;         __builtin_amdgcn_global_load_lds((const unsigned*)((const char*)(gbase) + (voff)[_i]), (PG8_LAS unsigned*)(lds + (bufoff) + ldsw + _i * 8192), 16, 0, 0); } while (0)
; #define PG8_LDA(dst, b, h) do { _Pragma("unroll") for (int m = 0; m < 4; ++m) _Pragma("unroll") for (int k = 0; k < 2; ++k) dst[m][k] = *(const PG8_LAS bf16x8*)(lds + PG8_SA(b, h) + aoff + m * 2048 + k * 1024); } while (0)
; #define PG8_LDB(dst, b, h) do { _Pragma("unroll") for (int n = 0; n < 2; ++n) _Pragma("unroll") for (int k = 0; k < 2; ++k) dst[n][k] = *(const PG8_LAS bf16x8*)(lds + PG8_SB(b, h) + boff + n * 2048 + k * 1024); } while (0)
; #define PG8_MMA(ai, bj, At, Bt) do { __builtin_amdgcn_s_setprio(1); _Pragma("unroll") for (int m = 0; m < 4; ++m) _Pragma("unroll") for (int n = 0; n < 2; ++n) _Pragma("unroll") for (int k = 0; k < 2; ++k) \
;         acc[ai][bj][m][n] = __builtin_amdgcn_mfma_f32_16x16x32_bf16(Bt[n][k], At[m][k], acc[ai][bj][m][n], 0, 0, 0); __builtin_amdgcn_s_setprio(0); } while (0)
; #define PG8_WAIT_V(n) asm volatile("s_waitcnt vmcnt(" #n ")" ::: "memory")
; #define PG8_WAIT_L(n) asm volatile("s_waitcnt lgkmcnt(" #n ")" ::: "memory")
; template <class Epi, class Sched, bool ALIGN_EPI = false, bool SP2 = false>
; __device__ __forceinline__ void gemm_phase(PG8_LAS unsigned char* lds, const Gemm g, const Sched& S, const Epi& E) {
;     ...
;         for (; t < tend; t += 2) {
;             const bool last = (t == nt - 2);
;             const char* a1 = cA + (size_t)(t + 1) * kstep;
;             const char* a2 = last ? nA : cA + (size_t)(t + 2) * kstep; const char* b2 = last ? nB : cB + (size_t)(t + 2) * kstep;
;             const char* a3 = a2 + kstep; const char* b3 = b2 + kstep;
;             if (last && has_next) S.a_ready(nxt);
;             if constexpr (SP2) {
;             PG8_LDB(B0, 0, 0); PG8_LDB(B1, 0, 1); PG8_SCHED; PG8_LDA(At, 0, 0); PG8_STAGE(PG8_SA(1, 1), a1 + hstep, voffA);
;             PG8_WAIT_V(8); PG8_WAIT_L(0); PG8_BAR; PG8_MMA(0, 0, At, B0); PG8_MMA(0, 1, At, B1); PG8_BAR; PG8_SCHED;
;             PG8_LDA(At, 0, 1); PG8_STAGE(PG8_SB(0, 0), b2, voffB); PG8_STAGE(PG8_SB(0, 1), b2 + hstep, voffB); PG8_STAGE(PG8_SA(0, 0), a2, voffA);
;             PG8_WAIT_V(8); PG8_WAIT_L(0); PG8_BAR; PG8_MMA(1, 0, At, B0); PG8_MMA(1, 1, At, B1); PG8_BAR; PG8_SCHED;
.LBB0_115:
	ds_read_b128 v[154:157], v150
	ds_read_b128 v[158:161], v150 offset:1024
	ds_read_b128 v[162:165], v150 offset:2048
	ds_read_b128 v[166:169], v150 offset:3072
	ds_read_b128 v[170:173], v151
	ds_read_b128 v[174:177], v151 offset:1024
	ds_read_b128 v[180:183], v151 offset:2048
	ds_read_b128 v[184:187], v151 offset:3072
	s_add_u32 s50, s48, 0x4000
	s_addc_u32 s51, s49, 0
	s_cmp_eq_u32 s76, 60
	s_cselect_b32 s74, s64, s50
	s_cselect_b32 s75, s25, s51
	s_cselect_b32 s72, s65, s68
	s_cselect_b32 s73, s19, s69
	s_add_u32 s50, s74, 0x8000
	s_addc_u32 s51, s75, 0
	s_sub_u32 s50, s48, 0x4000
	s_subb_u32 s51, s49, 0
	v_lshl_add_u64 v[224:225], s[50:51], 0, v[130:131]
	s_mov_b32 m0, s58
	s_nop 0
	global_load_lds_dwordx4 v[224:225], off
	v_lshl_add_u64 v[224:225], s[50:51], 0, v[134:135]
	s_mov_b32 m0, s59
	s_nop 0
	global_load_lds_dwordx4 v[224:225], off
	v_lshl_add_u64 v[224:225], s[48:49], 0, v[140:141]
	s_add_i32 m0, s28, 0xc000
	ds_read_b128 v[188:191], v152
	ds_read_b128 v[196:199], v152 offset:1024
	ds_read_b128 v[200:203], v152 offset:2048
	ds_read_b128 v[204:207], v152 offset:3072
	ds_read_b128 v[208:211], v152 offset:4096
	ds_read_b128 v[212:215], v152 offset:5120
	ds_read_b128 v[216:219], v152 offset:6144
	ds_read_b128 v[220:223], v152 offset:7168
	global_load_lds_dwordx4 v[224:225], off
	v_lshl_add_u64 v[224:225], s[48:49], 0, v[142:143]
	s_add_i32 m0, s28, 0xe000
	s_nop 0
	global_load_lds_dwordx4 v[224:225], off
	s_waitcnt vmcnt(8)
	s_waitcnt lgkmcnt(0)
	s_barrier
	s_setprio 1
	s_waitcnt lgkmcnt(0)
	v_mfma_f32_16x16x32_bf16 v[126:129], v[154:157], v[188:191], v[126:129]
	v_mfma_f32_16x16x32_bf16 v[118:121], v[162:165], v[188:191], v[118:121]
	v_mfma_f32_16x16x32_bf16 v[110:113], v[154:157], v[200:203], v[110:113]
	v_mfma_f32_16x16x32_bf16 v[102:105], v[162:165], v[200:203], v[102:105]
	v_mfma_f32_16x16x32_bf16 v[94:97], v[154:157], v[208:211], v[94:97]
	v_mfma_f32_16x16x32_bf16 v[86:89], v[162:165], v[208:211], v[86:89]
	v_mfma_f32_16x16x32_bf16 v[78:81], v[154:157], v[216:219], v[78:81]
	v_mfma_f32_16x16x32_bf16 v[70:73], v[162:165], v[216:219], v[70:73]
	v_mfma_f32_16x16x32_bf16 v[126:129], v[158:161], v[196:199], v[126:129]
	v_mfma_f32_16x16x32_bf16 v[118:121], v[166:169], v[196:199], v[118:121]
	v_mfma_f32_16x16x32_bf16 v[110:113], v[158:161], v[204:207], v[110:113]
	v_mfma_f32_16x16x32_bf16 v[102:105], v[166:169], v[204:207], v[102:105]
	v_mfma_f32_16x16x32_bf16 v[94:97], v[158:161], v[212:215], v[94:97]
	v_mfma_f32_16x16x32_bf16 v[86:89], v[166:169], v[212:215], v[86:89]
	v_mfma_f32_16x16x32_bf16 v[78:81], v[158:161], v[220:223], v[78:81]
	v_mfma_f32_16x16x32_bf16 v[70:73], v[166:169], v[220:223], v[70:73]
	s_setprio 0
	s_setprio 1
	v_mfma_f32_16x16x32_bf16 v[122:125], v[170:173], v[188:191], v[122:125]
	v_mfma_f32_16x16x32_bf16 v[114:117], v[180:183], v[188:191], v[114:117]
	v_mfma_f32_16x16x32_bf16 v[106:109], v[170:173], v[200:203], v[106:109]
	v_mfma_f32_16x16x32_bf16 v[98:101], v[180:183], v[200:203], v[98:101]
	v_mfma_f32_16x16x32_bf16 v[90:93], v[170:173], v[208:211], v[90:93]
	v_mfma_f32_16x16x32_bf16 v[82:85], v[180:183], v[208:211], v[82:85]
	v_mfma_f32_16x16x32_bf16 v[74:77], v[170:173], v[216:219], v[74:77]
	v_mfma_f32_16x16x32_bf16 v[66:69], v[180:183], v[216:219], v[66:69]
	v_mfma_f32_16x16x32_bf16 v[122:125], v[174:177], v[196:199], v[122:125]
	v_mfma_f32_16x16x32_bf16 v[114:117], v[184:187], v[196:199], v[114:117]
	v_mfma_f32_16x16x32_bf16 v[106:109], v[174:177], v[204:207], v[106:109]
	v_mfma_f32_16x16x32_bf16 v[98:101], v[184:187], v[204:207], v[98:101]
	v_mfma_f32_16x16x32_bf16 v[90:93], v[174:177], v[212:215], v[90:93]
	s_setprio 2
	s_barrier
	v_mfma_f32_16x16x32_bf16 v[82:85], v[184:187], v[212:215], v[82:85]
	v_mfma_f32_16x16x32_bf16 v[74:77], v[174:177], v[220:223], v[74:77]
	v_mfma_f32_16x16x32_bf16 v[66:69], v[184:187], v[220:223], v[66:69]
	s_setprio 0
	s_add_i32 s77, s61, s3
	v_lshl_add_u64 v[224:225], s[72:73], 0, v[132:133]
	s_mov_b32 m0, s77
	ds_read_b128 v[188:191], v152 offset:16384
	ds_read_b128 v[196:199], v152 offset:17408
	ds_read_b128 v[200:203], v152 offset:18432
	ds_read_b128 v[204:207], v152 offset:19456
	ds_read_b128 v[208:211], v152 offset:20480
	ds_read_b128 v[212:215], v152 offset:21504
	ds_read_b128 v[216:219], v152 offset:22528
	ds_read_b128 v[220:223], v152 offset:23552
	global_load_lds_dwordx4 v[224:225], off
	s_add_i32 m0, s77, 0x2000
	s_add_u32 s78, s72, 0x4000
	v_lshl_add_u64 v[224:225], s[72:73], 0, v[136:137]
	s_addc_u32 s79, s73, 0
	s_add_i32 s77, s62, s3
	global_load_lds_dwordx4 v[224:225], off
	v_lshl_add_u64 v[224:225], s[78:79], 0, v[132:133]
	s_mov_b32 m0, s77
	s_nop 0
	global_load_lds_dwordx4 v[224:225], off
	v_lshl_add_u64 v[224:225], s[78:79], 0, v[136:137]
	s_add_i32 m0, s77, 0x2000
	s_nop 0
	global_load_lds_dwordx4 v[224:225], off
	s_waitcnt vmcnt(6)
	s_waitcnt lgkmcnt(0)
	s_barrier
; #define PG8_STAGE(bufoff, gbase, voff) do { _Pragma("unroll") for (int _i = 0; _i < 2; ++_i) \
;         __builtin_amdgcn_global_load_lds((const unsigned*)((const char*)(gbase) + (voff)[_i]), (PG8_LAS unsigned*)(lds + (bufoff) + ldsw + _i * 8192), 16, 0, 0); } while (0)
; #define PG8_LDA(dst, b, h) do { _Pragma("unroll") for (int m = 0; m < 4; ++m) _Pragma("unroll") for (int k = 0; k < 2; ++k) dst[m][k] = *(const PG8_LAS bf16x8*)(lds + PG8_SA(b, h) + aoff + m * 2048 + k * 1024); } while (0)
; #define PG8_LDB(dst, b, h) do { _Pragma("unroll") for (int n = 0; n < 2; ++n) _Pragma("unroll") for (int k = 0; k < 2; ++k) dst[n][k] = *(const PG8_LAS bf16x8*)(lds + PG8_SB(b, h) + boff + n * 2048 + k * 1024); } while (0)
; #define PG8_MMA(ai, bj, At, Bt) do { __builtin_amdgcn_s_setprio(1); _Pragma("unroll") for (int m = 0; m < 4; ++m) _Pragma("unroll") for (int n = 0; n < 2; ++n) _Pragma("unroll") for (int k = 0; k < 2; ++k) \
;         acc[ai][bj][m][n] = __builtin_amdgcn_mfma_f32_16x16x32_bf16(Bt[n][k], At[m][k], acc[ai][bj][m][n], 0, 0, 0); __builtin_amdgcn_s_setprio(0); } while (0)
; #define PG8_WAIT_V(n) asm volatile("s_waitcnt vmcnt(" #n ")" ::: "memory")
; #define PG8_WAIT_L(n) asm volatile("s_waitcnt lgkmcnt(" #n ")" ::: "memory")
; #define PG8_BAR __builtin_amdgcn_s_barrier()
; #define PG8_SCHED __builtin_amdgcn_sched_barrier(0)
; template <class Epi, class Sched, bool ALIGN_EPI = false, bool SP2 = false>
; __device__ __forceinline__ void gemm_phase(PG8_LAS unsigned char* lds, const Gemm g, const Sched& S, const Epi& E) {
;     ...
;             PG8_WAIT_V(8); PG8_WAIT_L(0); PG8_BAR; PG8_MMA(1, 0, At, B0); PG8_MMA(1, 1, At, B1); PG8_BAR; PG8_SCHED;
;             PG8_LDB(B0, 1, 0); PG8_LDB(B1, 1, 1); PG8_SCHED; PG8_LDA(At, 1, 0); PG8_STAGE(PG8_SA(0, 1), a2 + hstep, voffA);
;             PG8_WAIT_V(8); PG8_WAIT_L(0); PG8_BAR; PG8_MMA(0, 0, At, B0); PG8_MMA(0, 1, At, B1); PG8_BAR; PG8_SCHED;
;             PG8_LDA(At, 1, 1); PG8_STAGE(PG8_SB(1, 0), b3, voffB); PG8_STAGE(PG8_SB(1, 1), b3 + hstep, voffB); PG8_STAGE(PG8_SA(1, 0), a3, voffA);
;             PG8_WAIT_V(8); PG8_WAIT_L(0); PG8_BAR; PG8_MMA(1, 0, At, B0); PG8_MMA(1, 1, At, B1); PG8_BAR; PG8_SCHED;
	s_setprio 1
	s_waitcnt lgkmcnt(0)
	v_mfma_f32_16x16x32_bf16 v[62:65], v[154:157], v[188:191], v[62:65]
	v_mfma_f32_16x16x32_bf16 v[54:57], v[162:165], v[188:191], v[54:57]
	v_mfma_f32_16x16x32_bf16 v[46:49], v[154:157], v[200:203], v[46:49]
	v_mfma_f32_16x16x32_bf16 v[38:41], v[162:165], v[200:203], v[38:41]
	v_mfma_f32_16x16x32_bf16 v[30:33], v[154:157], v[208:211], v[30:33]
	v_mfma_f32_16x16x32_bf16 v[22:25], v[162:165], v[208:211], v[22:25]
	v_mfma_f32_16x16x32_bf16 v[14:17], v[154:157], v[216:219], v[14:17]
	v_mfma_f32_16x16x32_bf16 v[6:9], v[162:165], v[216:219], v[6:9]
	v_mfma_f32_16x16x32_bf16 v[62:65], v[158:161], v[196:199], v[62:65]
	v_mfma_f32_16x16x32_bf16 v[54:57], v[166:169], v[196:199], v[54:57]
	v_mfma_f32_16x16x32_bf16 v[46:49], v[158:161], v[204:207], v[46:49]
	v_mfma_f32_16x16x32_bf16 v[38:41], v[166:169], v[204:207], v[38:41]
	v_mfma_f32_16x16x32_bf16 v[30:33], v[158:161], v[212:215], v[30:33]
	v_mfma_f32_16x16x32_bf16 v[22:25], v[166:169], v[212:215], v[22:25]
	v_mfma_f32_16x16x32_bf16 v[14:17], v[158:161], v[220:223], v[14:17]
	v_mfma_f32_16x16x32_bf16 v[6:9], v[166:169], v[220:223], v[6:9]
	s_setprio 0
	s_setprio 1
	v_mfma_f32_16x16x32_bf16 v[58:61], v[170:173], v[188:191], v[58:61]
	v_mfma_f32_16x16x32_bf16 v[50:53], v[180:183], v[188:191], v[50:53]
	v_mfma_f32_16x16x32_bf16 v[42:45], v[170:173], v[200:203], v[42:45]
	v_mfma_f32_16x16x32_bf16 v[34:37], v[180:183], v[200:203], v[34:37]
	v_mfma_f32_16x16x32_bf16 v[26:29], v[170:173], v[208:211], v[26:29]
	v_mfma_f32_16x16x32_bf16 v[18:21], v[180:183], v[208:211], v[18:21]
	v_mfma_f32_16x16x32_bf16 v[10:13], v[170:173], v[216:219], v[10:13]
	v_mfma_f32_16x16x32_bf16 v[2:5], v[180:183], v[216:219], v[2:5]
	v_mfma_f32_16x16x32_bf16 v[58:61], v[174:177], v[196:199], v[58:61]
	v_mfma_f32_16x16x32_bf16 v[50:53], v[184:187], v[196:199], v[50:53]
	v_mfma_f32_16x16x32_bf16 v[42:45], v[174:177], v[204:207], v[42:45]
	v_mfma_f32_16x16x32_bf16 v[34:37], v[184:187], v[204:207], v[34:37]
	v_mfma_f32_16x16x32_bf16 v[26:29], v[174:177], v[212:215], v[26:29]
	s_setprio 2
	s_barrier
	v_mfma_f32_16x16x32_bf16 v[18:21], v[184:187], v[212:215], v[18:21]
	v_mfma_f32_16x16x32_bf16 v[10:13], v[174:177], v[220:223], v[10:13]
	v_mfma_f32_16x16x32_bf16 v[2:5], v[184:187], v[220:223], v[2:5]
	s_setprio 0
	s_add_i32 s77, 0, 0x18000
	v_add_u32_e32 v138, s77, v148
	s_add_i32 s78, 0, 0x1c000
	ds_read_b128 v[154:157], v138
	ds_read_b128 v[158:161], v138 offset:1024
	ds_read_b128 v[162:165], v138 offset:2048
	ds_read_b128 v[166:169], v138 offset:3072
	v_add_u32_e32 v138, s78, v148
	ds_read_b128 v[170:173], v138
	ds_read_b128 v[174:177], v138 offset:1024
	ds_read_b128 v[180:183], v138 offset:2048
	ds_read_b128 v[184:187], v138 offset:3072
	v_lshl_add_u64 v[224:225], s[74:75], 0, v[130:131]
	s_mov_b32 m0, s28
	s_nop 0
	global_load_lds_dwordx4 v[224:225], off
	v_lshl_add_u64 v[224:225], s[74:75], 0, v[134:135]
	s_mov_b32 m0, s29
	s_nop 0
	global_load_lds_dwordx4 v[224:225], off
	s_add_u32 s74, s74, 0x4000
	s_addc_u32 s75, s75, 0
	s_mov_b32 m0, s30
	v_lshl_add_u64 v[224:225], s[74:75], 0, v[130:131]
	ds_read_b128 v[188:191], v152 offset:32768
	ds_read_b128 v[196:199], v152 offset:33792
	ds_read_b128 v[200:203], v152 offset:34816
	ds_read_b128 v[204:207], v152 offset:35840
	ds_read_b128 v[208:211], v152 offset:36864
	ds_read_b128 v[212:215], v152 offset:37888
	ds_read_b128 v[216:219], v152 offset:38912
	ds_read_b128 v[220:223], v152 offset:39936
	global_load_lds_dwordx4 v[224:225], off
	v_lshl_add_u64 v[224:225], s[74:75], 0, v[134:135]
	s_mov_b32 m0, s31
	s_nop 0
	global_load_lds_dwordx4 v[224:225], off
	s_waitcnt vmcnt(8)
	s_waitcnt lgkmcnt(0)
	s_barrier
	s_setprio 1
	s_waitcnt lgkmcnt(0)
	v_mfma_f32_16x16x32_bf16 v[126:129], v[154:157], v[188:191], v[126:129]
	v_mfma_f32_16x16x32_bf16 v[118:121], v[162:165], v[188:191], v[118:121]
	v_mfma_f32_16x16x32_bf16 v[110:113], v[154:157], v[200:203], v[110:113]
	v_mfma_f32_16x16x32_bf16 v[102:105], v[162:165], v[200:203], v[102:105]
	v_mfma_f32_16x16x32_bf16 v[94:97], v[154:157], v[208:211], v[94:97]
	v_mfma_f32_16x16x32_bf16 v[86:89], v[162:165], v[208:211], v[86:89]
	v_mfma_f32_16x16x32_bf16 v[78:81], v[154:157], v[216:219], v[78:81]
	v_mfma_f32_16x16x32_bf16 v[70:73], v[162:165], v[216:219], v[70:73]
	v_mfma_f32_16x16x32_bf16 v[126:129], v[158:161], v[196:199], v[126:129]
	v_mfma_f32_16x16x32_bf16 v[118:121], v[166:169], v[196:199], v[118:121]
	v_mfma_f32_16x16x32_bf16 v[110:113], v[158:161], v[204:207], v[110:113]
	v_mfma_f32_16x16x32_bf16 v[102:105], v[166:169], v[204:207], v[102:105]
	v_mfma_f32_16x16x32_bf16 v[94:97], v[158:161], v[212:215], v[94:97]
	v_mfma_f32_16x16x32_bf16 v[86:89], v[166:169], v[212:215], v[86:89]
	v_mfma_f32_16x16x32_bf16 v[78:81], v[158:161], v[220:223], v[78:81]
	v_mfma_f32_16x16x32_bf16 v[70:73], v[166:169], v[220:223], v[70:73]
	s_setprio 0
	s_setprio 1
	v_mfma_f32_16x16x32_bf16 v[122:125], v[170:173], v[188:191], v[122:125]
	v_mfma_f32_16x16x32_bf16 v[114:117], v[180:183], v[188:191], v[114:117]
	v_mfma_f32_16x16x32_bf16 v[106:109], v[170:173], v[200:203], v[106:109]
	v_mfma_f32_16x16x32_bf16 v[98:101], v[180:183], v[200:203], v[98:101]
	v_mfma_f32_16x16x32_bf16 v[90:93], v[170:173], v[208:211], v[90:93]
	v_mfma_f32_16x16x32_bf16 v[82:85], v[180:183], v[208:211], v[82:85]
	v_mfma_f32_16x16x32_bf16 v[74:77], v[170:173], v[216:219], v[74:77]
	v_mfma_f32_16x16x32_bf16 v[66:69], v[180:183], v[216:219], v[66:69]
	v_mfma_f32_16x16x32_bf16 v[122:125], v[174:177], v[196:199], v[122:125]
	v_mfma_f32_16x16x32_bf16 v[114:117], v[184:187], v[196:199], v[114:117]
	v_mfma_f32_16x16x32_bf16 v[106:109], v[174:177], v[204:207], v[106:109]
	v_mfma_f32_16x16x32_bf16 v[98:101], v[184:187], v[204:207], v[98:101]
	v_mfma_f32_16x16x32_bf16 v[90:93], v[174:177], v[212:215], v[90:93]
	s_setprio 2
	s_barrier
; #define PG8_STAGE(bufoff, gbase, voff) do { _Pragma("unroll") for (int _i = 0; _i < 2; ++_i) \
;         __builtin_amdgcn_global_load_lds((const unsigned*)((const char*)(gbase) + (voff)[_i]), (PG8_LAS unsigned*)(lds + (bufoff) + ldsw + _i * 8192), 16, 0, 0); } while (0)
; #define PG8_LDA(dst, b, h) do { _Pragma("unroll") for (int m = 0; m < 4; ++m) _Pragma("unroll") for (int k = 0; k < 2; ++k) dst[m][k] = *(const PG8_LAS bf16x8*)(lds + PG8_SA(b, h) + aoff + m * 2048 + k * 1024); } while (0)
; #define PG8_MMA(ai, bj, At, Bt) do { __builtin_amdgcn_s_setprio(1); _Pragma("unroll") for (int m = 0; m < 4; ++m) _Pragma("unroll") for (int n = 0; n < 2; ++n) _Pragma("unroll") for (int k = 0; k < 2; ++k) \
;         acc[ai][bj][m][n] = __builtin_amdgcn_mfma_f32_16x16x32_bf16(Bt[n][k], At[m][k], acc[ai][bj][m][n], 0, 0, 0); __builtin_amdgcn_s_setprio(0); } while (0)
; #define PG8_WAIT_V(n) asm volatile("s_waitcnt vmcnt(" #n ")" ::: "memory")
; #define PG8_WAIT_L(n) asm volatile("s_waitcnt lgkmcnt(" #n ")" ::: "memory")
; #define PG8_BAR __builtin_amdgcn_s_barrier()
; #define PG8_SCHED __builtin_amdgcn_sched_barrier(0)
; template <class Epi, class Sched, bool ALIGN_EPI = false, bool SP2 = false>
; __device__ __forceinline__ void gemm_phase(PG8_LAS unsigned char* lds, const Gemm g, const Sched& S, const Epi& E) {
;     ...
;             PG8_WAIT_V(8); PG8_WAIT_L(0); PG8_BAR; PG8_MMA(0, 0, At, B0); PG8_MMA(0, 1, At, B1); PG8_BAR; PG8_SCHED;
;             PG8_LDA(At, 1, 1); PG8_STAGE(PG8_SB(1, 0), b3, voffB); PG8_STAGE(PG8_SB(1, 1), b3 + hstep, voffB); PG8_STAGE(PG8_SA(1, 0), a3, voffA);
;             PG8_WAIT_V(8); PG8_WAIT_L(0); PG8_BAR; PG8_MMA(1, 0, At, B0); PG8_MMA(1, 1, At, B1); PG8_BAR; PG8_SCHED;
;     ...
;         if constexpr (ALIGN_EPI) { if (wr == 0) PG8_BAR; }
	v_mfma_f32_16x16x32_bf16 v[82:85], v[184:187], v[212:215], v[82:85]
	v_mfma_f32_16x16x32_bf16 v[74:77], v[174:177], v[220:223], v[74:77]
	v_mfma_f32_16x16x32_bf16 v[66:69], v[184:187], v[220:223], v[66:69]
	s_setprio 0
	s_add_u32 s74, s72, 0x8000
	s_addc_u32 s75, s73, 0
	s_add_i32 s77, s77, s3
	v_lshl_add_u64 v[224:225], s[74:75], 0, v[132:133]
	s_mov_b32 m0, s77
	ds_read_b128 v[188:191], v152 offset:49152
	ds_read_b128 v[196:199], v152 offset:50176
	ds_read_b128 v[200:203], v152 offset:51200
	ds_read_b128 v[204:207], v152 offset:52224
	ds_read_b128 v[208:211], v152 offset:53248
	ds_read_b128 v[212:215], v152 offset:54272
	ds_read_b128 v[216:219], v152 offset:55296
	ds_read_b128 v[220:223], v152 offset:56320
	global_load_lds_dwordx4 v[224:225], off
	s_add_i32 m0, s77, 0x2000
	s_add_u32 s72, s72, 0xc000
	v_lshl_add_u64 v[224:225], s[74:75], 0, v[136:137]
	s_addc_u32 s73, s73, 0
	s_add_i32 s74, s78, s3
	global_load_lds_dwordx4 v[224:225], off
	v_lshl_add_u64 v[224:225], s[72:73], 0, v[132:133]
	s_mov_b32 m0, s74
	s_nop 0
	global_load_lds_dwordx4 v[224:225], off
	v_lshl_add_u64 v[224:225], s[72:73], 0, v[136:137]
	s_add_i32 m0, s74, 0x2000
	s_nop 0
	global_load_lds_dwordx4 v[224:225], off
	s_waitcnt vmcnt(6)
	s_waitcnt lgkmcnt(0)
	s_barrier
	s_setprio 1
	s_waitcnt lgkmcnt(0)
	v_mfma_f32_16x16x32_bf16 v[62:65], v[154:157], v[188:191], v[62:65]
	v_mfma_f32_16x16x32_bf16 v[54:57], v[162:165], v[188:191], v[54:57]
	v_mfma_f32_16x16x32_bf16 v[46:49], v[154:157], v[200:203], v[46:49]
	v_mfma_f32_16x16x32_bf16 v[38:41], v[162:165], v[200:203], v[38:41]
	v_mfma_f32_16x16x32_bf16 v[30:33], v[154:157], v[208:211], v[30:33]
	v_mfma_f32_16x16x32_bf16 v[22:25], v[162:165], v[208:211], v[22:25]
	v_mfma_f32_16x16x32_bf16 v[14:17], v[154:157], v[216:219], v[14:17]
	v_mfma_f32_16x16x32_bf16 v[6:9], v[162:165], v[216:219], v[6:9]
	v_mfma_f32_16x16x32_bf16 v[62:65], v[158:161], v[196:199], v[62:65]
	v_mfma_f32_16x16x32_bf16 v[54:57], v[166:169], v[196:199], v[54:57]
	v_mfma_f32_16x16x32_bf16 v[46:49], v[158:161], v[204:207], v[46:49]
	v_mfma_f32_16x16x32_bf16 v[38:41], v[166:169], v[204:207], v[38:41]
	v_mfma_f32_16x16x32_bf16 v[30:33], v[158:161], v[212:215], v[30:33]
	v_mfma_f32_16x16x32_bf16 v[22:25], v[166:169], v[212:215], v[22:25]
	v_mfma_f32_16x16x32_bf16 v[14:17], v[158:161], v[220:223], v[14:17]
	v_mfma_f32_16x16x32_bf16 v[6:9], v[166:169], v[220:223], v[6:9]
	s_setprio 0
	s_setprio 1
	v_mfma_f32_16x16x32_bf16 v[58:61], v[170:173], v[188:191], v[58:61]
	v_mfma_f32_16x16x32_bf16 v[50:53], v[180:183], v[188:191], v[50:53]
	v_mfma_f32_16x16x32_bf16 v[42:45], v[170:173], v[200:203], v[42:45]
	v_mfma_f32_16x16x32_bf16 v[34:37], v[180:183], v[200:203], v[34:37]
	v_mfma_f32_16x16x32_bf16 v[26:29], v[170:173], v[208:211], v[26:29]
	v_mfma_f32_16x16x32_bf16 v[18:21], v[180:183], v[208:211], v[18:21]
	v_mfma_f32_16x16x32_bf16 v[10:13], v[170:173], v[216:219], v[10:13]
	v_mfma_f32_16x16x32_bf16 v[2:5], v[180:183], v[216:219], v[2:5]
	v_mfma_f32_16x16x32_bf16 v[58:61], v[174:177], v[196:199], v[58:61]
	v_mfma_f32_16x16x32_bf16 v[50:53], v[184:187], v[196:199], v[50:53]
	v_mfma_f32_16x16x32_bf16 v[42:45], v[174:177], v[204:207], v[42:45]
	v_mfma_f32_16x16x32_bf16 v[34:37], v[184:187], v[204:207], v[34:37]
	v_mfma_f32_16x16x32_bf16 v[26:29], v[174:177], v[212:215], v[26:29]
	s_setprio 2
	s_barrier
	v_mfma_f32_16x16x32_bf16 v[18:21], v[184:187], v[212:215], v[18:21]
	v_mfma_f32_16x16x32_bf16 v[10:13], v[174:177], v[220:223], v[10:13]
	v_mfma_f32_16x16x32_bf16 v[2:5], v[184:187], v[220:223], v[2:5]
	s_setprio 0
	s_add_i32 s76, s76, 2
	s_add_u32 s48, s48, 0x10000
	s_addc_u32 s49, s49, 0
	s_add_u32 s68, s68, 0x10000
	s_addc_u32 s69, s69, 0
	s_cmp_gt_u32 s76, 61
	s_cbranch_scc0 .LBB0_115
	s_and_b64 vcc, exec, s[14:15]
	s_cbranch_vccz .LBB0_118
	s_barrier

; #define PG8_STAGE(bufoff, gbase, voff) do { _Pragma("unroll") for (int _i = 0; _i < 2; ++_i) \
;         __builtin_amdgcn_global_load_lds((const unsigned*)((const char*)(gbase) + (voff)[_i]), (PG8_LAS unsigned*)(lds + (bufoff) + ldsw + _i * 8192), 16, 0, 0); } while (0)
; #define PG8_LDA(dst, b, h) do { _Pragma("unroll") for (int m = 0; m < 4; ++m) _Pragma("unroll") for (int k = 0; k < 2; ++k) dst[m][k] = *(const PG8_LAS bf16x8*)(lds + PG8_SA(b, h) + aoff + m * 2048 + k * 1024); } while (0)
; #define PG8_LDB(dst, b, h) do { _Pragma("unroll") for (int n = 0; n < 2; ++n) _Pragma("unroll") for (int k = 0; k < 2; ++k) dst[n][k] = *(const PG8_LAS bf16x8*)(lds + PG8_SB(b, h) + boff + n * 2048 + k * 1024); } while (0)
; #define PG8_MMA(ai, bj, At, Bt) do { __builtin_amdgcn_s_setprio(1); _Pragma("unroll") for (int m = 0; m < 4; ++m) _Pragma("unroll") for (int n = 0; n < 2; ++n) _Pragma("unroll") for (int k = 0; k < 2; ++k) \
;         acc[ai][bj][m][n] = __builtin_amdgcn_mfma_f32_16x16x32_bf16(Bt[n][k], At[m][k], acc[ai][bj][m][n], 0, 0, 0); __builtin_amdgcn_s_setprio(0); } while (0)
; #define PG8_WAIT_V(n) asm volatile("s_waitcnt vmcnt(" #n ")" ::: "memory")
; #define PG8_WAIT_L(n) asm volatile("s_waitcnt lgkmcnt(" #n ")" ::: "memory")
; template <class Epi, class Sched, bool ALIGN_EPI = false, bool SP2 = false>
; __device__ __forceinline__ void gemm_phase(PG8_LAS unsigned char* lds, const Gemm g, const Sched& S, const Epi& E) {
;     ...
;         for (; t < tend; t += 2) {
;             const bool last = (t == nt - 2);
;             const char* a1 = cA + (size_t)(t + 1) * kstep;
;             const char* a2 = last ? nA : cA + (size_t)(t + 2) * kstep; const char* b2 = last ? nB : cB + (size_t)(t + 2) * kstep;
;             const char* a3 = a2 + kstep; const char* b3 = b2 + kstep;
;             if (last && has_next) S.a_ready(nxt);
;             if constexpr (SP2) {
;             PG8_LDB(B0, 0, 0); PG8_LDB(B1, 0, 1); PG8_SCHED; PG8_LDA(At, 0, 0); PG8_STAGE(PG8_SA(1, 1), a1 + hstep, voffA);
;             PG8_WAIT_V(8); PG8_WAIT_L(0); PG8_BAR; PG8_MMA(0, 0, At, B0); PG8_MMA(0, 1, At, B1); PG8_BAR; PG8_SCHED;
;             PG8_LDA(At, 0, 1); PG8_STAGE(PG8_SB(0, 0), b2, voffB); PG8_STAGE(PG8_SB(0, 1), b2 + hstep, voffB); PG8_STAGE(PG8_SA(0, 0), a2, voffA);
;             PG8_WAIT_V(8); PG8_WAIT_L(0); PG8_BAR; PG8_MMA(1, 0, At, B0); PG8_MMA(1, 1, At, B1); PG8_BAR; PG8_SCHED;
.LBB0_200:
	ds_read_b128 v[148:151], v154
	ds_read_b128 v[158:161], v154 offset:1024
	ds_read_b128 v[162:165], v154 offset:2048
	ds_read_b128 v[166:169], v154 offset:3072
	ds_read_b128 v[170:173], v155
	ds_read_b128 v[174:177], v155 offset:1024
	ds_read_b128 v[180:183], v155 offset:2048
	ds_read_b128 v[184:187], v155 offset:3072
	s_add_u32 s46, s44, 0x4000
	s_addc_u32 s47, s45, 0
	s_cmpk_eq_i32 s76, 0xa8
	s_cselect_b32 s50, s6, s46
	s_cselect_b32 s51, s7, s47
	s_cselect_b32 s48, s24, s74
	s_cselect_b32 s49, s25, s75
	s_add_u32 s46, s50, 0x8000
	s_addc_u32 s47, s51, 0
	s_sub_u32 s46, s44, 0x4000
	s_subb_u32 s47, s45, 0
	v_lshl_add_u64 v[224:225], s[46:47], 0, v[130:131]
	s_mov_b32 m0, s57
	s_nop 0
	global_load_lds_dwordx4 v[224:225], off
	v_lshl_add_u64 v[224:225], s[46:47], 0, v[134:135]
	s_mov_b32 m0, s58
	s_nop 0
	global_load_lds_dwordx4 v[224:225], off
	v_lshl_add_u64 v[224:225], s[44:45], 0, v[140:141]
	s_add_i32 m0, s26, 0xc000
	ds_read_b128 v[188:191], v156
	ds_read_b128 v[196:199], v156 offset:1024
	ds_read_b128 v[200:203], v156 offset:2048
	ds_read_b128 v[204:207], v156 offset:3072
	ds_read_b128 v[208:211], v156 offset:4096
	ds_read_b128 v[212:215], v156 offset:5120
	ds_read_b128 v[216:219], v156 offset:6144
	ds_read_b128 v[220:223], v156 offset:7168
	global_load_lds_dwordx4 v[224:225], off
	v_lshl_add_u64 v[224:225], s[44:45], 0, v[142:143]
	s_add_i32 m0, s26, 0xe000
	s_nop 0
	global_load_lds_dwordx4 v[224:225], off
	s_waitcnt vmcnt(8)
	s_waitcnt lgkmcnt(0)
	s_barrier
	s_setprio 1
	s_waitcnt lgkmcnt(0)
	v_mfma_f32_16x16x32_bf16 v[126:129], v[148:151], v[188:191], v[126:129]
	v_mfma_f32_16x16x32_bf16 v[122:125], v[162:165], v[188:191], v[122:125]
	v_mfma_f32_16x16x32_bf16 v[110:113], v[148:151], v[200:203], v[110:113]
	v_mfma_f32_16x16x32_bf16 v[106:109], v[162:165], v[200:203], v[106:109]
	v_mfma_f32_16x16x32_bf16 v[94:97], v[148:151], v[208:211], v[94:97]
	v_mfma_f32_16x16x32_bf16 v[90:93], v[162:165], v[208:211], v[90:93]
	v_mfma_f32_16x16x32_bf16 v[78:81], v[148:151], v[216:219], v[78:81]
	v_mfma_f32_16x16x32_bf16 v[74:77], v[162:165], v[216:219], v[74:77]
	v_mfma_f32_16x16x32_bf16 v[126:129], v[158:161], v[196:199], v[126:129]
	v_mfma_f32_16x16x32_bf16 v[122:125], v[166:169], v[196:199], v[122:125]
	v_mfma_f32_16x16x32_bf16 v[110:113], v[158:161], v[204:207], v[110:113]
	v_mfma_f32_16x16x32_bf16 v[106:109], v[166:169], v[204:207], v[106:109]
	v_mfma_f32_16x16x32_bf16 v[94:97], v[158:161], v[212:215], v[94:97]
	v_mfma_f32_16x16x32_bf16 v[90:93], v[166:169], v[212:215], v[90:93]
	v_mfma_f32_16x16x32_bf16 v[78:81], v[158:161], v[220:223], v[78:81]
	v_mfma_f32_16x16x32_bf16 v[74:77], v[166:169], v[220:223], v[74:77]
	s_setprio 0
	s_setprio 1
	v_mfma_f32_16x16x32_bf16 v[118:121], v[170:173], v[188:191], v[118:121]
	v_mfma_f32_16x16x32_bf16 v[114:117], v[180:183], v[188:191], v[114:117]
	v_mfma_f32_16x16x32_bf16 v[102:105], v[170:173], v[200:203], v[102:105]
	v_mfma_f32_16x16x32_bf16 v[98:101], v[180:183], v[200:203], v[98:101]
	v_mfma_f32_16x16x32_bf16 v[86:89], v[170:173], v[208:211], v[86:89]
	v_mfma_f32_16x16x32_bf16 v[82:85], v[180:183], v[208:211], v[82:85]
	v_mfma_f32_16x16x32_bf16 v[70:73], v[170:173], v[216:219], v[70:73]
	v_mfma_f32_16x16x32_bf16 v[66:69], v[180:183], v[216:219], v[66:69]
	v_mfma_f32_16x16x32_bf16 v[118:121], v[174:177], v[196:199], v[118:121]
	v_mfma_f32_16x16x32_bf16 v[114:117], v[184:187], v[196:199], v[114:117]
	v_mfma_f32_16x16x32_bf16 v[102:105], v[174:177], v[204:207], v[102:105]
	v_mfma_f32_16x16x32_bf16 v[98:101], v[184:187], v[204:207], v[98:101]
	v_mfma_f32_16x16x32_bf16 v[86:89], v[174:177], v[212:215], v[86:89]
	s_setprio 2
	s_barrier
	v_mfma_f32_16x16x32_bf16 v[82:85], v[184:187], v[212:215], v[82:85]
	v_mfma_f32_16x16x32_bf16 v[70:73], v[174:177], v[220:223], v[70:73]
	v_mfma_f32_16x16x32_bf16 v[66:69], v[184:187], v[220:223], v[66:69]
	s_setprio 0
	s_add_i32 s77, s59, s3
	v_lshl_add_u64 v[224:225], s[48:49], 0, v[132:133]
	s_mov_b32 m0, s77
	ds_read_b128 v[188:191], v156 offset:16384
	ds_read_b128 v[196:199], v156 offset:17408
	ds_read_b128 v[200:203], v156 offset:18432
	ds_read_b128 v[204:207], v156 offset:19456
	ds_read_b128 v[208:211], v156 offset:20480
	ds_read_b128 v[212:215], v156 offset:21504
	ds_read_b128 v[216:219], v156 offset:22528
	ds_read_b128 v[220:223], v156 offset:23552
	global_load_lds_dwordx4 v[224:225], off
	s_add_i32 m0, s77, 0x2000
	s_add_u32 s78, s48, 0x4000
	v_lshl_add_u64 v[224:225], s[48:49], 0, v[136:137]
	s_addc_u32 s79, s49, 0
	s_add_i32 s77, s61, s3
	global_load_lds_dwordx4 v[224:225], off
	v_lshl_add_u64 v[224:225], s[78:79], 0, v[132:133]
	s_mov_b32 m0, s77
	s_nop 0
	global_load_lds_dwordx4 v[224:225], off
	v_lshl_add_u64 v[224:225], s[78:79], 0, v[136:137]
	s_add_i32 m0, s77, 0x2000
	s_nop 0
	global_load_lds_dwordx4 v[224:225], off
	s_waitcnt vmcnt(6)
	s_waitcnt lgkmcnt(0)
	s_barrier
; #define PG8_STAGE(bufoff, gbase, voff) do { _Pragma("unroll") for (int _i = 0; _i < 2; ++_i) \
;         __builtin_amdgcn_global_load_lds((const unsigned*)((const char*)(gbase) + (voff)[_i]), (PG8_LAS unsigned*)(lds + (bufoff) + ldsw + _i * 8192), 16, 0, 0); } while (0)
; #define PG8_LDA(dst, b, h) do { _Pragma("unroll") for (int m = 0; m < 4; ++m) _Pragma("unroll") for (int k = 0; k < 2; ++k) dst[m][k] = *(const PG8_LAS bf16x8*)(lds + PG8_SA(b, h) + aoff + m * 2048 + k * 1024); } while (0)
; #define PG8_LDB(dst, b, h) do { _Pragma("unroll") for (int n = 0; n < 2; ++n) _Pragma("unroll") for (int k = 0; k < 2; ++k) dst[n][k] = *(const PG8_LAS bf16x8*)(lds + PG8_SB(b, h) + boff + n * 2048 + k * 1024); } while (0)
; #define PG8_MMA(ai, bj, At, Bt) do { __builtin_amdgcn_s_setprio(1); _Pragma("unroll") for (int m = 0; m < 4; ++m) _Pragma("unroll") for (int n = 0; n < 2; ++n) _Pragma("unroll") for (int k = 0; k < 2; ++k) \
;         acc[ai][bj][m][n] = __builtin_amdgcn_mfma_f32_16x16x32_bf16(Bt[n][k], At[m][k], acc[ai][bj][m][n], 0, 0, 0); __builtin_amdgcn_s_setprio(0); } while (0)
; #define PG8_WAIT_V(n) asm volatile("s_waitcnt vmcnt(" #n ")" ::: "memory")
; #define PG8_WAIT_L(n) asm volatile("s_waitcnt lgkmcnt(" #n ")" ::: "memory")
; #define PG8_BAR __builtin_amdgcn_s_barrier()
; #define PG8_SCHED __builtin_amdgcn_sched_barrier(0)
; template <class Epi, class Sched, bool ALIGN_EPI = false, bool SP2 = false>
; __device__ __forceinline__ void gemm_phase(PG8_LAS unsigned char* lds, const Gemm g, const Sched& S, const Epi& E) {
;     ...
;             PG8_WAIT_V(8); PG8_WAIT_L(0); PG8_BAR; PG8_MMA(1, 0, At, B0); PG8_MMA(1, 1, At, B1); PG8_BAR; PG8_SCHED;
;             PG8_LDB(B0, 1, 0); PG8_LDB(B1, 1, 1); PG8_SCHED; PG8_LDA(At, 1, 0); PG8_STAGE(PG8_SA(0, 1), a2 + hstep, voffA);
;             PG8_WAIT_V(8); PG8_WAIT_L(0); PG8_BAR; PG8_MMA(0, 0, At, B0); PG8_MMA(0, 1, At, B1); PG8_BAR; PG8_SCHED;
;             PG8_LDA(At, 1, 1); PG8_STAGE(PG8_SB(1, 0), b3, voffB); PG8_STAGE(PG8_SB(1, 1), b3 + hstep, voffB); PG8_STAGE(PG8_SA(1, 0), a3, voffA);
;             PG8_WAIT_V(8); PG8_WAIT_L(0); PG8_BAR; PG8_MMA(1, 0, At, B0); PG8_MMA(1, 1, At, B1); PG8_BAR; PG8_SCHED;
	s_setprio 1
	s_waitcnt lgkmcnt(0)
	v_mfma_f32_16x16x32_bf16 v[62:65], v[148:151], v[188:191], v[62:65]
	v_mfma_f32_16x16x32_bf16 v[58:61], v[162:165], v[188:191], v[58:61]
	v_mfma_f32_16x16x32_bf16 v[46:49], v[148:151], v[200:203], v[46:49]
	v_mfma_f32_16x16x32_bf16 v[42:45], v[162:165], v[200:203], v[42:45]
	v_mfma_f32_16x16x32_bf16 v[30:33], v[148:151], v[208:211], v[30:33]
	v_mfma_f32_16x16x32_bf16 v[26:29], v[162:165], v[208:211], v[26:29]
	v_mfma_f32_16x16x32_bf16 v[14:17], v[148:151], v[216:219], v[14:17]
	v_mfma_f32_16x16x32_bf16 v[10:13], v[162:165], v[216:219], v[10:13]
	v_mfma_f32_16x16x32_bf16 v[62:65], v[158:161], v[196:199], v[62:65]
	v_mfma_f32_16x16x32_bf16 v[58:61], v[166:169], v[196:199], v[58:61]
	v_mfma_f32_16x16x32_bf16 v[46:49], v[158:161], v[204:207], v[46:49]
	v_mfma_f32_16x16x32_bf16 v[42:45], v[166:169], v[204:207], v[42:45]
	v_mfma_f32_16x16x32_bf16 v[30:33], v[158:161], v[212:215], v[30:33]
	v_mfma_f32_16x16x32_bf16 v[26:29], v[166:169], v[212:215], v[26:29]
	v_mfma_f32_16x16x32_bf16 v[14:17], v[158:161], v[220:223], v[14:17]
	v_mfma_f32_16x16x32_bf16 v[10:13], v[166:169], v[220:223], v[10:13]
	s_setprio 0
	s_setprio 1
	v_mfma_f32_16x16x32_bf16 v[54:57], v[170:173], v[188:191], v[54:57]
	v_mfma_f32_16x16x32_bf16 v[50:53], v[180:183], v[188:191], v[50:53]
	v_mfma_f32_16x16x32_bf16 v[38:41], v[170:173], v[200:203], v[38:41]
	v_mfma_f32_16x16x32_bf16 v[34:37], v[180:183], v[200:203], v[34:37]
	v_mfma_f32_16x16x32_bf16 v[22:25], v[170:173], v[208:211], v[22:25]
	v_mfma_f32_16x16x32_bf16 v[18:21], v[180:183], v[208:211], v[18:21]
	v_mfma_f32_16x16x32_bf16 v[6:9], v[170:173], v[216:219], v[6:9]
	v_mfma_f32_16x16x32_bf16 v[2:5], v[180:183], v[216:219], v[2:5]
	v_mfma_f32_16x16x32_bf16 v[54:57], v[174:177], v[196:199], v[54:57]
	v_mfma_f32_16x16x32_bf16 v[50:53], v[184:187], v[196:199], v[50:53]
	v_mfma_f32_16x16x32_bf16 v[38:41], v[174:177], v[204:207], v[38:41]
	v_mfma_f32_16x16x32_bf16 v[34:37], v[184:187], v[204:207], v[34:37]
	v_mfma_f32_16x16x32_bf16 v[22:25], v[174:177], v[212:215], v[22:25]
	s_setprio 2
	s_barrier
	v_mfma_f32_16x16x32_bf16 v[18:21], v[184:187], v[212:215], v[18:21]
	v_mfma_f32_16x16x32_bf16 v[6:9], v[174:177], v[220:223], v[6:9]
	v_mfma_f32_16x16x32_bf16 v[2:5], v[184:187], v[220:223], v[2:5]
	s_setprio 0
	s_add_i32 s77, 0, 0x18000
	v_add_u32_e32 v138, s77, v153
	s_add_i32 s78, 0, 0x1c000
	ds_read_b128 v[148:151], v138
	ds_read_b128 v[158:161], v138 offset:1024
	ds_read_b128 v[162:165], v138 offset:2048
	ds_read_b128 v[166:169], v138 offset:3072
	v_add_u32_e32 v138, s78, v153
	ds_read_b128 v[170:173], v138
	ds_read_b128 v[174:177], v138 offset:1024
	ds_read_b128 v[180:183], v138 offset:2048
	ds_read_b128 v[184:187], v138 offset:3072
	v_lshl_add_u64 v[224:225], s[50:51], 0, v[130:131]
	s_mov_b32 m0, s26
	s_nop 0
	global_load_lds_dwordx4 v[224:225], off
	v_lshl_add_u64 v[224:225], s[50:51], 0, v[134:135]
	s_mov_b32 m0, s27
	s_nop 0
	global_load_lds_dwordx4 v[224:225], off
	s_add_u32 s50, s50, 0x4000
	s_addc_u32 s51, s51, 0
	s_mov_b32 m0, s28
	v_lshl_add_u64 v[224:225], s[50:51], 0, v[130:131]
	ds_read_b128 v[188:191], v156 offset:32768
	ds_read_b128 v[196:199], v156 offset:33792
	ds_read_b128 v[200:203], v156 offset:34816
	ds_read_b128 v[204:207], v156 offset:35840
	ds_read_b128 v[208:211], v156 offset:36864
	ds_read_b128 v[212:215], v156 offset:37888
	ds_read_b128 v[216:219], v156 offset:38912
	ds_read_b128 v[220:223], v156 offset:39936
	global_load_lds_dwordx4 v[224:225], off
	v_lshl_add_u64 v[224:225], s[50:51], 0, v[134:135]
	s_mov_b32 m0, s29
	s_nop 0
	global_load_lds_dwordx4 v[224:225], off
	s_waitcnt vmcnt(8)
	s_waitcnt lgkmcnt(0)
	s_barrier
	s_setprio 1
	s_waitcnt lgkmcnt(0)
	v_mfma_f32_16x16x32_bf16 v[126:129], v[148:151], v[188:191], v[126:129]
	v_mfma_f32_16x16x32_bf16 v[122:125], v[162:165], v[188:191], v[122:125]
	v_mfma_f32_16x16x32_bf16 v[110:113], v[148:151], v[200:203], v[110:113]
	v_mfma_f32_16x16x32_bf16 v[106:109], v[162:165], v[200:203], v[106:109]
	v_mfma_f32_16x16x32_bf16 v[94:97], v[148:151], v[208:211], v[94:97]
	v_mfma_f32_16x16x32_bf16 v[90:93], v[162:165], v[208:211], v[90:93]
	v_mfma_f32_16x16x32_bf16 v[78:81], v[148:151], v[216:219], v[78:81]
	v_mfma_f32_16x16x32_bf16 v[74:77], v[162:165], v[216:219], v[74:77]
	v_mfma_f32_16x16x32_bf16 v[126:129], v[158:161], v[196:199], v[126:129]
	v_mfma_f32_16x16x32_bf16 v[122:125], v[166:169], v[196:199], v[122:125]
	v_mfma_f32_16x16x32_bf16 v[110:113], v[158:161], v[204:207], v[110:113]
	v_mfma_f32_16x16x32_bf16 v[106:109], v[166:169], v[204:207], v[106:109]
	v_mfma_f32_16x16x32_bf16 v[94:97], v[158:161], v[212:215], v[94:97]
	v_mfma_f32_16x16x32_bf16 v[90:93], v[166:169], v[212:215], v[90:93]
	v_mfma_f32_16x16x32_bf16 v[78:81], v[158:161], v[220:223], v[78:81]
	v_mfma_f32_16x16x32_bf16 v[74:77], v[166:169], v[220:223], v[74:77]
	s_setprio 0
	s_setprio 1
	v_mfma_f32_16x16x32_bf16 v[118:121], v[170:173], v[188:191], v[118:121]
	v_mfma_f32_16x16x32_bf16 v[114:117], v[180:183], v[188:191], v[114:117]
	v_mfma_f32_16x16x32_bf16 v[102:105], v[170:173], v[200:203], v[102:105]
	v_mfma_f32_16x16x32_bf16 v[98:101], v[180:183], v[200:203], v[98:101]
	v_mfma_f32_16x16x32_bf16 v[86:89], v[170:173], v[208:211], v[86:89]
	v_mfma_f32_16x16x32_bf16 v[82:85], v[180:183], v[208:211], v[82:85]
	v_mfma_f32_16x16x32_bf16 v[70:73], v[170:173], v[216:219], v[70:73]
	v_mfma_f32_16x16x32_bf16 v[66:69], v[180:183], v[216:219], v[66:69]
	v_mfma_f32_16x16x32_bf16 v[118:121], v[174:177], v[196:199], v[118:121]
	v_mfma_f32_16x16x32_bf16 v[114:117], v[184:187], v[196:199], v[114:117]
	v_mfma_f32_16x16x32_bf16 v[102:105], v[174:177], v[204:207], v[102:105]
	v_mfma_f32_16x16x32_bf16 v[98:101], v[184:187], v[204:207], v[98:101]
	v_mfma_f32_16x16x32_bf16 v[86:89], v[174:177], v[212:215], v[86:89]
	s_setprio 2
	s_barrier
; #define PG8_STAGE(bufoff, gbase, voff) do { _Pragma("unroll") for (int _i = 0; _i < 2; ++_i) \
;         __builtin_amdgcn_global_load_lds((const unsigned*)((const char*)(gbase) + (voff)[_i]), (PG8_LAS unsigned*)(lds + (bufoff) + ldsw + _i * 8192), 16, 0, 0); } while (0)
; #define PG8_LDA(dst, b, h) do { _Pragma("unroll") for (int m = 0; m < 4; ++m) _Pragma("unroll") for (int k = 0; k < 2; ++k) dst[m][k] = *(const PG8_LAS bf16x8*)(lds + PG8_SA(b, h) + aoff + m * 2048 + k * 1024); } while (0)
; #define PG8_MMA(ai, bj, At, Bt) do { __builtin_amdgcn_s_setprio(1); _Pragma("unroll") for (int m = 0; m < 4; ++m) _Pragma("unroll") for (int n = 0; n < 2; ++n) _Pragma("unroll") for (int k = 0; k < 2; ++k) \
;         acc[ai][bj][m][n] = __builtin_amdgcn_mfma_f32_16x16x32_bf16(Bt[n][k], At[m][k], acc[ai][bj][m][n], 0, 0, 0); __builtin_amdgcn_s_setprio(0); } while (0)
; #define PG8_WAIT_V(n) asm volatile("s_waitcnt vmcnt(" #n ")" ::: "memory")
; #define PG8_WAIT_L(n) asm volatile("s_waitcnt lgkmcnt(" #n ")" ::: "memory")
; #define PG8_BAR __builtin_amdgcn_s_barrier()
; #define PG8_SCHED __builtin_amdgcn_sched_barrier(0)
; template <class Epi, class Sched, bool ALIGN_EPI = false, bool SP2 = false>
; __device__ __forceinline__ void gemm_phase(PG8_LAS unsigned char* lds, const Gemm g, const Sched& S, const Epi& E) {
;     ...
;             PG8_WAIT_V(8); PG8_WAIT_L(0); PG8_BAR; PG8_MMA(0, 0, At, B0); PG8_MMA(0, 1, At, B1); PG8_BAR; PG8_SCHED;
;             PG8_LDA(At, 1, 1); PG8_STAGE(PG8_SB(1, 0), b3, voffB); PG8_STAGE(PG8_SB(1, 1), b3 + hstep, voffB); PG8_STAGE(PG8_SA(1, 0), a3, voffA);
;             PG8_WAIT_V(8); PG8_WAIT_L(0); PG8_BAR; PG8_MMA(1, 0, At, B0); PG8_MMA(1, 1, At, B1); PG8_BAR; PG8_SCHED;
;     ...
;         if constexpr (ALIGN_EPI) { if (wr == 0) PG8_BAR; }
	v_mfma_f32_16x16x32_bf16 v[82:85], v[184:187], v[212:215], v[82:85]
	v_mfma_f32_16x16x32_bf16 v[70:73], v[174:177], v[220:223], v[70:73]
	v_mfma_f32_16x16x32_bf16 v[66:69], v[184:187], v[220:223], v[66:69]
	s_setprio 0
	s_add_u32 s50, s48, 0x8000
	s_addc_u32 s51, s49, 0
	s_add_i32 s77, s77, s3
	v_lshl_add_u64 v[224:225], s[50:51], 0, v[132:133]
	s_mov_b32 m0, s77
	ds_read_b128 v[188:191], v156 offset:49152
	ds_read_b128 v[196:199], v156 offset:50176
	ds_read_b128 v[200:203], v156 offset:51200
	ds_read_b128 v[204:207], v156 offset:52224
	ds_read_b128 v[208:211], v156 offset:53248
	ds_read_b128 v[212:215], v156 offset:54272
	ds_read_b128 v[216:219], v156 offset:55296
	ds_read_b128 v[220:223], v156 offset:56320
	global_load_lds_dwordx4 v[224:225], off
	s_add_i32 m0, s77, 0x2000
	s_add_u32 s48, s48, 0xc000
	v_lshl_add_u64 v[224:225], s[50:51], 0, v[136:137]
	s_addc_u32 s49, s49, 0
	s_add_i32 s50, s78, s3
	global_load_lds_dwordx4 v[224:225], off
	v_lshl_add_u64 v[224:225], s[48:49], 0, v[132:133]
	s_mov_b32 m0, s50
	s_nop 0
	global_load_lds_dwordx4 v[224:225], off
	v_lshl_add_u64 v[224:225], s[48:49], 0, v[136:137]
	s_add_i32 m0, s50, 0x2000
	s_nop 0
	global_load_lds_dwordx4 v[224:225], off
	s_waitcnt vmcnt(6)
	s_waitcnt lgkmcnt(0)
	s_barrier
	s_setprio 1
	s_waitcnt lgkmcnt(0)
	v_mfma_f32_16x16x32_bf16 v[62:65], v[148:151], v[188:191], v[62:65]
	v_mfma_f32_16x16x32_bf16 v[58:61], v[162:165], v[188:191], v[58:61]
	v_mfma_f32_16x16x32_bf16 v[46:49], v[148:151], v[200:203], v[46:49]
	v_mfma_f32_16x16x32_bf16 v[42:45], v[162:165], v[200:203], v[42:45]
	v_mfma_f32_16x16x32_bf16 v[30:33], v[148:151], v[208:211], v[30:33]
	v_mfma_f32_16x16x32_bf16 v[26:29], v[162:165], v[208:211], v[26:29]
	v_mfma_f32_16x16x32_bf16 v[14:17], v[148:151], v[216:219], v[14:17]
	v_mfma_f32_16x16x32_bf16 v[10:13], v[162:165], v[216:219], v[10:13]
	v_mfma_f32_16x16x32_bf16 v[62:65], v[158:161], v[196:199], v[62:65]
	v_mfma_f32_16x16x32_bf16 v[58:61], v[166:169], v[196:199], v[58:61]
	v_mfma_f32_16x16x32_bf16 v[46:49], v[158:161], v[204:207], v[46:49]
	v_mfma_f32_16x16x32_bf16 v[42:45], v[166:169], v[204:207], v[42:45]
	v_mfma_f32_16x16x32_bf16 v[30:33], v[158:161], v[212:215], v[30:33]
	v_mfma_f32_16x16x32_bf16 v[26:29], v[166:169], v[212:215], v[26:29]
	v_mfma_f32_16x16x32_bf16 v[14:17], v[158:161], v[220:223], v[14:17]
	v_mfma_f32_16x16x32_bf16 v[10:13], v[166:169], v[220:223], v[10:13]
	s_setprio 0
	s_setprio 1
	v_mfma_f32_16x16x32_bf16 v[54:57], v[170:173], v[188:191], v[54:57]
	v_mfma_f32_16x16x32_bf16 v[50:53], v[180:183], v[188:191], v[50:53]
	v_mfma_f32_16x16x32_bf16 v[38:41], v[170:173], v[200:203], v[38:41]
	v_mfma_f32_16x16x32_bf16 v[34:37], v[180:183], v[200:203], v[34:37]
	v_mfma_f32_16x16x32_bf16 v[22:25], v[170:173], v[208:211], v[22:25]
	v_mfma_f32_16x16x32_bf16 v[18:21], v[180:183], v[208:211], v[18:21]
	v_mfma_f32_16x16x32_bf16 v[6:9], v[170:173], v[216:219], v[6:9]
	v_mfma_f32_16x16x32_bf16 v[2:5], v[180:183], v[216:219], v[2:5]
	v_mfma_f32_16x16x32_bf16 v[54:57], v[174:177], v[196:199], v[54:57]
	v_mfma_f32_16x16x32_bf16 v[50:53], v[184:187], v[196:199], v[50:53]
	v_mfma_f32_16x16x32_bf16 v[38:41], v[174:177], v[204:207], v[38:41]
	v_mfma_f32_16x16x32_bf16 v[34:37], v[184:187], v[204:207], v[34:37]
	v_mfma_f32_16x16x32_bf16 v[22:25], v[174:177], v[212:215], v[22:25]
	s_setprio 2
	s_barrier
	v_mfma_f32_16x16x32_bf16 v[18:21], v[184:187], v[212:215], v[18:21]
	v_mfma_f32_16x16x32_bf16 v[6:9], v[174:177], v[220:223], v[6:9]
	v_mfma_f32_16x16x32_bf16 v[2:5], v[184:187], v[220:223], v[2:5]
	s_setprio 0
	s_add_i32 s76, s76, 2
	s_add_u32 s44, s44, 0x10000
	s_addc_u32 s45, s45, 0
	s_add_u32 s74, s74, 0x10000
	s_addc_u32 s75, s75, 0
	s_cmpk_gt_u32 s76, 0xa9
	s_cbranch_scc0 .LBB0_200
	s_and_b64 vcc, exec, s[18:19]
	s_cbranch_vccz .LBB0_203
	s_barrier

; #define PG8_STAGE(bufoff, gbase, voff) do { _Pragma("unroll") for (int _i = 0; _i < 2; ++_i) \
;         __builtin_amdgcn_global_load_lds((const unsigned*)((const char*)(gbase) + (voff)[_i]), (PG8_LAS unsigned*)(lds + (bufoff) + ldsw + _i * 8192), 16, 0, 0); } while (0)
; #define PG8_LDA(dst, b, h) do { _Pragma("unroll") for (int m = 0; m < 4; ++m) _Pragma("unroll") for (int k = 0; k < 2; ++k) dst[m][k] = *(const PG8_LAS bf16x8*)(lds + PG8_SA(b, h) + aoff + m * 2048 + k * 1024); } while (0)
; #define PG8_LDB(dst, b, h) do { _Pragma("unroll") for (int n = 0; n < 2; ++n) _Pragma("unroll") for (int k = 0; k < 2; ++k) dst[n][k] = *(const PG8_LAS bf16x8*)(lds + PG8_SB(b, h) + boff + n * 2048 + k * 1024); } while (0)
; #define PG8_MMA(ai, bj, At, Bt) do { __builtin_amdgcn_s_setprio(1); _Pragma("unroll") for (int m = 0; m < 4; ++m) _Pragma("unroll") for (int n = 0; n < 2; ++n) _Pragma("unroll") for (int k = 0; k < 2; ++k) \
;         acc[ai][bj][m][n] = __builtin_amdgcn_mfma_f32_16x16x32_bf16(Bt[n][k], At[m][k], acc[ai][bj][m][n], 0, 0, 0); __builtin_amdgcn_s_setprio(0); } while (0)
; #define PG8_WAIT_V(n) asm volatile("s_waitcnt vmcnt(" #n ")" ::: "memory")
; #define PG8_WAIT_L(n) asm volatile("s_waitcnt lgkmcnt(" #n ")" ::: "memory")
; template <class Epi, class Sched, bool ALIGN_EPI = false, bool SP2 = false>
; __device__ __forceinline__ void gemm_phase(PG8_LAS unsigned char* lds, const Gemm g, const Sched& S, const Epi& E) {
;     ...
;         for (; t < tend; t += 2) {
;             const bool last = (t == nt - 2);
;             const char* a1 = cA + (size_t)(t + 1) * kstep;
;             const char* a2 = last ? nA : cA + (size_t)(t + 2) * kstep; const char* b2 = last ? nB : cB + (size_t)(t + 2) * kstep;
;             const char* a3 = a2 + kstep; const char* b3 = b2 + kstep;
;             if (last && has_next) S.a_ready(nxt);
;             if constexpr (SP2) {
;             PG8_LDB(B0, 0, 0); PG8_LDB(B1, 0, 1); PG8_SCHED; PG8_LDA(At, 0, 0); PG8_STAGE(PG8_SA(1, 1), a1 + hstep, voffA);
;             PG8_WAIT_V(8); PG8_WAIT_L(0); PG8_BAR; PG8_MMA(0, 0, At, B0); PG8_MMA(0, 1, At, B1); PG8_BAR; PG8_SCHED;
;             PG8_LDA(At, 0, 1); PG8_STAGE(PG8_SB(0, 0), b2, voffB); PG8_STAGE(PG8_SB(0, 1), b2 + hstep, voffB); PG8_STAGE(PG8_SA(0, 0), a2, voffA);
;             PG8_WAIT_V(8); PG8_WAIT_L(0); PG8_BAR; PG8_MMA(1, 0, At, B0); PG8_MMA(1, 1, At, B1); PG8_BAR; PG8_SCHED;
.LBB0_290:
	ds_read_b128 v[146:149], v162
	ds_read_b128 v[150:153], v162 offset:1024
	ds_read_b128 v[154:157], v162 offset:2048
	ds_read_b128 v[168:171], v162 offset:3072
	ds_read_b128 v[172:175], v163
	ds_read_b128 v[180:183], v163 offset:1024
	ds_read_b128 v[184:187], v163 offset:2048
	ds_read_b128 v[188:191], v163 offset:3072
	s_add_u32 s59, s72, 0x4000
	s_addc_u32 s62, s73, 0
	s_cmp_eq_u32 s58, 60
	s_cselect_b32 s78, s19, s59
	s_cselect_b32 s79, s5, s62
	s_cselect_b32 s76, s26, s33
	s_cselect_b32 s77, s17, s56
	s_add_u32 s74, s78, 0x8000
	s_addc_u32 s75, s79, 0
	s_sub_u32 s74, s72, 0x4000
	s_subb_u32 s75, s73, 0
	v_lshl_add_u64 v[158:159], s[74:75], 0, v[130:131]
	s_mov_b32 m0, s51
	s_nop 0
	global_load_lds_dwordx4 v[158:159], off
	v_lshl_add_u64 v[158:159], s[74:75], 0, v[134:135]
	s_mov_b32 m0, s57
	s_nop 0
	global_load_lds_dwordx4 v[158:159], off
	v_lshl_add_u64 v[158:159], s[72:73], 0, v[138:139]
	s_add_i32 m0, s15, 0xc000
	ds_read_b128 v[198:201], v164
	ds_read_b128 v[202:205], v164 offset:1024
	ds_read_b128 v[206:209], v164 offset:2048
	ds_read_b128 v[210:213], v164 offset:3072
	ds_read_b128 v[214:217], v164 offset:4096
	ds_read_b128 v[218:221], v164 offset:5120
	ds_read_b128 v[222:225], v164 offset:6144
	ds_read_b128 v[226:229], v164 offset:7168
	global_load_lds_dwordx4 v[158:159], off
	v_lshl_add_u64 v[158:159], s[72:73], 0, v[140:141]
	s_add_i32 m0, s15, 0xe000
	s_nop 0
	global_load_lds_dwordx4 v[158:159], off
	s_waitcnt vmcnt(8)
	s_waitcnt lgkmcnt(0)
	s_barrier
	s_setprio 1
	s_waitcnt lgkmcnt(0)
	v_mfma_f32_16x16x32_bf16 v[126:129], v[146:149], v[198:201], v[126:129]
	v_mfma_f32_16x16x32_bf16 v[122:125], v[154:157], v[198:201], v[122:125]
	v_mfma_f32_16x16x32_bf16 v[110:113], v[146:149], v[206:209], v[110:113]
	v_mfma_f32_16x16x32_bf16 v[106:109], v[154:157], v[206:209], v[106:109]
	v_mfma_f32_16x16x32_bf16 v[94:97], v[146:149], v[214:217], v[94:97]
	v_mfma_f32_16x16x32_bf16 v[90:93], v[154:157], v[214:217], v[90:93]
	v_mfma_f32_16x16x32_bf16 v[78:81], v[146:149], v[222:225], v[78:81]
	v_mfma_f32_16x16x32_bf16 v[74:77], v[154:157], v[222:225], v[74:77]
	v_mfma_f32_16x16x32_bf16 v[126:129], v[150:153], v[202:205], v[126:129]
	v_mfma_f32_16x16x32_bf16 v[122:125], v[168:171], v[202:205], v[122:125]
	v_mfma_f32_16x16x32_bf16 v[110:113], v[150:153], v[210:213], v[110:113]
	v_mfma_f32_16x16x32_bf16 v[106:109], v[168:171], v[210:213], v[106:109]
	v_mfma_f32_16x16x32_bf16 v[94:97], v[150:153], v[218:221], v[94:97]
	v_mfma_f32_16x16x32_bf16 v[90:93], v[168:171], v[218:221], v[90:93]
	v_mfma_f32_16x16x32_bf16 v[78:81], v[150:153], v[226:229], v[78:81]
	v_mfma_f32_16x16x32_bf16 v[74:77], v[168:171], v[226:229], v[74:77]
	s_setprio 0
	s_setprio 1
	v_mfma_f32_16x16x32_bf16 v[118:121], v[172:175], v[198:201], v[118:121]
	v_mfma_f32_16x16x32_bf16 v[114:117], v[184:187], v[198:201], v[114:117]
	v_mfma_f32_16x16x32_bf16 v[102:105], v[172:175], v[206:209], v[102:105]
	v_mfma_f32_16x16x32_bf16 v[98:101], v[184:187], v[206:209], v[98:101]
	v_mfma_f32_16x16x32_bf16 v[86:89], v[172:175], v[214:217], v[86:89]
	v_mfma_f32_16x16x32_bf16 v[82:85], v[184:187], v[214:217], v[82:85]
	v_mfma_f32_16x16x32_bf16 v[70:73], v[172:175], v[222:225], v[70:73]
	v_mfma_f32_16x16x32_bf16 v[66:69], v[184:187], v[222:225], v[66:69]
	v_mfma_f32_16x16x32_bf16 v[118:121], v[180:183], v[202:205], v[118:121]
	v_mfma_f32_16x16x32_bf16 v[114:117], v[188:191], v[202:205], v[114:117]
	v_mfma_f32_16x16x32_bf16 v[102:105], v[180:183], v[210:213], v[102:105]
	v_mfma_f32_16x16x32_bf16 v[98:101], v[188:191], v[210:213], v[98:101]
	v_mfma_f32_16x16x32_bf16 v[86:89], v[180:183], v[218:221], v[86:89]
	s_setprio 2
	s_barrier
	v_mfma_f32_16x16x32_bf16 v[82:85], v[188:191], v[218:221], v[82:85]
	v_mfma_f32_16x16x32_bf16 v[70:73], v[180:183], v[226:229], v[70:73]
	v_mfma_f32_16x16x32_bf16 v[66:69], v[188:191], v[226:229], v[66:69]
	s_setprio 0
	s_add_i32 s59, s81, s3
	v_lshl_add_u64 v[158:159], s[76:77], 0, v[132:133]
	s_mov_b32 m0, s59
	ds_read_b128 v[198:201], v164 offset:16384
	ds_read_b128 v[202:205], v164 offset:17408
	ds_read_b128 v[206:209], v164 offset:18432
	ds_read_b128 v[210:213], v164 offset:19456
	ds_read_b128 v[214:217], v164 offset:20480
	ds_read_b128 v[218:221], v164 offset:21504
	ds_read_b128 v[222:225], v164 offset:22528
	ds_read_b128 v[226:229], v164 offset:23552
	global_load_lds_dwordx4 v[158:159], off
	s_add_i32 m0, s59, 0x2000
	s_add_u32 s62, s76, 0x4000
	v_lshl_add_u64 v[158:159], s[76:77], 0, v[136:137]
	s_addc_u32 s63, s77, 0
	s_add_i32 s59, s82, s3
	global_load_lds_dwordx4 v[158:159], off
	v_lshl_add_u64 v[158:159], s[62:63], 0, v[132:133]
	s_mov_b32 m0, s59
	s_nop 0
	global_load_lds_dwordx4 v[158:159], off
	v_lshl_add_u64 v[158:159], s[62:63], 0, v[136:137]
	s_add_i32 m0, s59, 0x2000
	s_nop 0
	global_load_lds_dwordx4 v[158:159], off
	s_waitcnt vmcnt(6)
	s_waitcnt lgkmcnt(0)
	s_barrier
; #define PG8_STAGE(bufoff, gbase, voff) do { _Pragma("unroll") for (int _i = 0; _i < 2; ++_i) \
;         __builtin_amdgcn_global_load_lds((const unsigned*)((const char*)(gbase) + (voff)[_i]), (PG8_LAS unsigned*)(lds + (bufoff) + ldsw + _i * 8192), 16, 0, 0); } while (0)
; #define PG8_LDA(dst, b, h) do { _Pragma("unroll") for (int m = 0; m < 4; ++m) _Pragma("unroll") for (int k = 0; k < 2; ++k) dst[m][k] = *(const PG8_LAS bf16x8*)(lds + PG8_SA(b, h) + aoff + m * 2048 + k * 1024); } while (0)
; #define PG8_LDB(dst, b, h) do { _Pragma("unroll") for (int n = 0; n < 2; ++n) _Pragma("unroll") for (int k = 0; k < 2; ++k) dst[n][k] = *(const PG8_LAS bf16x8*)(lds + PG8_SB(b, h) + boff + n * 2048 + k * 1024); } while (0)
; #define PG8_MMA(ai, bj, At, Bt) do { __builtin_amdgcn_s_setprio(1); _Pragma("unroll") for (int m = 0; m < 4; ++m) _Pragma("unroll") for (int n = 0; n < 2; ++n) _Pragma("unroll") for (int k = 0; k < 2; ++k) \
;         acc[ai][bj][m][n] = __builtin_amdgcn_mfma_f32_16x16x32_bf16(Bt[n][k], At[m][k], acc[ai][bj][m][n], 0, 0, 0); __builtin_amdgcn_s_setprio(0); } while (0)
; #define PG8_WAIT_V(n) asm volatile("s_waitcnt vmcnt(" #n ")" ::: "memory")
; #define PG8_WAIT_L(n) asm volatile("s_waitcnt lgkmcnt(" #n ")" ::: "memory")
; #define PG8_BAR __builtin_amdgcn_s_barrier()
; #define PG8_SCHED __builtin_amdgcn_sched_barrier(0)
; template <class Epi, class Sched, bool ALIGN_EPI = false, bool SP2 = false>
; __device__ __forceinline__ void gemm_phase(PG8_LAS unsigned char* lds, const Gemm g, const Sched& S, const Epi& E) {
;     ...
;             PG8_WAIT_V(8); PG8_WAIT_L(0); PG8_BAR; PG8_MMA(1, 0, At, B0); PG8_MMA(1, 1, At, B1); PG8_BAR; PG8_SCHED;
;             PG8_LDB(B0, 1, 0); PG8_LDB(B1, 1, 1); PG8_SCHED; PG8_LDA(At, 1, 0); PG8_STAGE(PG8_SA(0, 1), a2 + hstep, voffA);
;             PG8_WAIT_V(8); PG8_WAIT_L(0); PG8_BAR; PG8_MMA(0, 0, At, B0); PG8_MMA(0, 1, At, B1); PG8_BAR; PG8_SCHED;
;             PG8_LDA(At, 1, 1); PG8_STAGE(PG8_SB(1, 0), b3, voffB); PG8_STAGE(PG8_SB(1, 1), b3 + hstep, voffB); PG8_STAGE(PG8_SA(1, 0), a3, voffA);
;             PG8_WAIT_V(8); PG8_WAIT_L(0); PG8_BAR; PG8_MMA(1, 0, At, B0); PG8_MMA(1, 1, At, B1); PG8_BAR; PG8_SCHED;
	s_setprio 1
	s_waitcnt lgkmcnt(0)
	v_mfma_f32_16x16x32_bf16 v[62:65], v[146:149], v[198:201], v[62:65]
	v_mfma_f32_16x16x32_bf16 v[58:61], v[154:157], v[198:201], v[58:61]
	v_mfma_f32_16x16x32_bf16 v[46:49], v[146:149], v[206:209], v[46:49]
	v_mfma_f32_16x16x32_bf16 v[42:45], v[154:157], v[206:209], v[42:45]
	v_mfma_f32_16x16x32_bf16 v[30:33], v[146:149], v[214:217], v[30:33]
	v_mfma_f32_16x16x32_bf16 v[26:29], v[154:157], v[214:217], v[26:29]
	v_mfma_f32_16x16x32_bf16 v[14:17], v[146:149], v[222:225], v[14:17]
	v_mfma_f32_16x16x32_bf16 v[10:13], v[154:157], v[222:225], v[10:13]
	v_mfma_f32_16x16x32_bf16 v[62:65], v[150:153], v[202:205], v[62:65]
	v_mfma_f32_16x16x32_bf16 v[58:61], v[168:171], v[202:205], v[58:61]
	v_mfma_f32_16x16x32_bf16 v[46:49], v[150:153], v[210:213], v[46:49]
	v_mfma_f32_16x16x32_bf16 v[42:45], v[168:171], v[210:213], v[42:45]
	v_mfma_f32_16x16x32_bf16 v[30:33], v[150:153], v[218:221], v[30:33]
	v_mfma_f32_16x16x32_bf16 v[26:29], v[168:171], v[218:221], v[26:29]
	v_mfma_f32_16x16x32_bf16 v[14:17], v[150:153], v[226:229], v[14:17]
	v_mfma_f32_16x16x32_bf16 v[10:13], v[168:171], v[226:229], v[10:13]
	s_setprio 0
	s_setprio 1
	v_mfma_f32_16x16x32_bf16 v[54:57], v[172:175], v[198:201], v[54:57]
	v_mfma_f32_16x16x32_bf16 v[50:53], v[184:187], v[198:201], v[50:53]
	v_mfma_f32_16x16x32_bf16 v[38:41], v[172:175], v[206:209], v[38:41]
	v_mfma_f32_16x16x32_bf16 v[34:37], v[184:187], v[206:209], v[34:37]
	v_mfma_f32_16x16x32_bf16 v[22:25], v[172:175], v[214:217], v[22:25]
	v_mfma_f32_16x16x32_bf16 v[18:21], v[184:187], v[214:217], v[18:21]
	v_mfma_f32_16x16x32_bf16 v[6:9], v[172:175], v[222:225], v[6:9]
	v_mfma_f32_16x16x32_bf16 v[2:5], v[184:187], v[222:225], v[2:5]
	v_mfma_f32_16x16x32_bf16 v[54:57], v[180:183], v[202:205], v[54:57]
	v_mfma_f32_16x16x32_bf16 v[50:53], v[188:191], v[202:205], v[50:53]
	v_mfma_f32_16x16x32_bf16 v[38:41], v[180:183], v[210:213], v[38:41]
	v_mfma_f32_16x16x32_bf16 v[34:37], v[188:191], v[210:213], v[34:37]
	v_mfma_f32_16x16x32_bf16 v[22:25], v[180:183], v[218:221], v[22:25]
	s_setprio 2
	s_barrier
	v_mfma_f32_16x16x32_bf16 v[18:21], v[188:191], v[218:221], v[18:21]
	v_mfma_f32_16x16x32_bf16 v[6:9], v[180:183], v[226:229], v[6:9]
	v_mfma_f32_16x16x32_bf16 v[2:5], v[188:191], v[226:229], v[2:5]
	s_setprio 0
	s_add_i32 s59, 0, 0x18000
	v_add_u32_e32 v158, s59, v160
	s_add_i32 s64, 0, 0x1c000
	ds_read_b128 v[146:149], v158
	ds_read_b128 v[150:153], v158 offset:1024
	ds_read_b128 v[154:157], v158 offset:2048
	ds_read_b128 v[168:171], v158 offset:3072
	v_add_u32_e32 v158, s64, v160
	ds_read_b128 v[172:175], v158
	ds_read_b128 v[180:183], v158 offset:1024
	ds_read_b128 v[184:187], v158 offset:2048
	ds_read_b128 v[188:191], v158 offset:3072
	v_lshl_add_u64 v[158:159], s[78:79], 0, v[130:131]
	s_mov_b32 m0, s15
	s_nop 0
	global_load_lds_dwordx4 v[158:159], off
	v_lshl_add_u64 v[158:159], s[78:79], 0, v[134:135]
	s_mov_b32 m0, s27
	s_nop 0
	global_load_lds_dwordx4 v[158:159], off
	s_add_u32 s62, s78, 0x4000
	s_addc_u32 s63, s79, 0
	s_mov_b32 m0, s28
	v_lshl_add_u64 v[158:159], s[62:63], 0, v[130:131]
	ds_read_b128 v[198:201], v164 offset:32768
	ds_read_b128 v[202:205], v164 offset:33792
	ds_read_b128 v[206:209], v164 offset:34816
	ds_read_b128 v[210:213], v164 offset:35840
	ds_read_b128 v[214:217], v164 offset:36864
	ds_read_b128 v[218:221], v164 offset:37888
	ds_read_b128 v[222:225], v164 offset:38912
	ds_read_b128 v[226:229], v164 offset:39936
	global_load_lds_dwordx4 v[158:159], off
	v_lshl_add_u64 v[158:159], s[62:63], 0, v[134:135]
	s_mov_b32 m0, s29
	s_nop 0
	global_load_lds_dwordx4 v[158:159], off
	s_waitcnt vmcnt(8)
	s_waitcnt lgkmcnt(0)
	s_barrier
	s_setprio 1
	s_waitcnt lgkmcnt(0)
	v_mfma_f32_16x16x32_bf16 v[126:129], v[146:149], v[198:201], v[126:129]
	v_mfma_f32_16x16x32_bf16 v[122:125], v[154:157], v[198:201], v[122:125]
	v_mfma_f32_16x16x32_bf16 v[110:113], v[146:149], v[206:209], v[110:113]
	v_mfma_f32_16x16x32_bf16 v[106:109], v[154:157], v[206:209], v[106:109]
	v_mfma_f32_16x16x32_bf16 v[94:97], v[146:149], v[214:217], v[94:97]
	v_mfma_f32_16x16x32_bf16 v[90:93], v[154:157], v[214:217], v[90:93]
	v_mfma_f32_16x16x32_bf16 v[78:81], v[146:149], v[222:225], v[78:81]
	v_mfma_f32_16x16x32_bf16 v[74:77], v[154:157], v[222:225], v[74:77]
	v_mfma_f32_16x16x32_bf16 v[126:129], v[150:153], v[202:205], v[126:129]
	v_mfma_f32_16x16x32_bf16 v[122:125], v[168:171], v[202:205], v[122:125]
	v_mfma_f32_16x16x32_bf16 v[110:113], v[150:153], v[210:213], v[110:113]
	v_mfma_f32_16x16x32_bf16 v[106:109], v[168:171], v[210:213], v[106:109]
	v_mfma_f32_16x16x32_bf16 v[94:97], v[150:153], v[218:221], v[94:97]
	v_mfma_f32_16x16x32_bf16 v[90:93], v[168:171], v[218:221], v[90:93]
	v_mfma_f32_16x16x32_bf16 v[78:81], v[150:153], v[226:229], v[78:81]
	v_mfma_f32_16x16x32_bf16 v[74:77], v[168:171], v[226:229], v[74:77]
	s_setprio 0
	s_setprio 1
	v_mfma_f32_16x16x32_bf16 v[118:121], v[172:175], v[198:201], v[118:121]
	v_mfma_f32_16x16x32_bf16 v[114:117], v[184:187], v[198:201], v[114:117]
	v_mfma_f32_16x16x32_bf16 v[102:105], v[172:175], v[206:209], v[102:105]
	v_mfma_f32_16x16x32_bf16 v[98:101], v[184:187], v[206:209], v[98:101]
	v_mfma_f32_16x16x32_bf16 v[86:89], v[172:175], v[214:217], v[86:89]
	v_mfma_f32_16x16x32_bf16 v[82:85], v[184:187], v[214:217], v[82:85]
	v_mfma_f32_16x16x32_bf16 v[70:73], v[172:175], v[222:225], v[70:73]
	v_mfma_f32_16x16x32_bf16 v[66:69], v[184:187], v[222:225], v[66:69]
	v_mfma_f32_16x16x32_bf16 v[118:121], v[180:183], v[202:205], v[118:121]
	v_mfma_f32_16x16x32_bf16 v[114:117], v[188:191], v[202:205], v[114:117]
	v_mfma_f32_16x16x32_bf16 v[102:105], v[180:183], v[210:213], v[102:105]
	v_mfma_f32_16x16x32_bf16 v[98:101], v[188:191], v[210:213], v[98:101]
	v_mfma_f32_16x16x32_bf16 v[86:89], v[180:183], v[218:221], v[86:89]
	s_setprio 2
	s_barrier
; #define PG8_STAGE(bufoff, gbase, voff) do { _Pragma("unroll") for (int _i = 0; _i < 2; ++_i) \
;         __builtin_amdgcn_global_load_lds((const unsigned*)((const char*)(gbase) + (voff)[_i]), (PG8_LAS unsigned*)(lds + (bufoff) + ldsw + _i * 8192), 16, 0, 0); } while (0)
; #define PG8_LDA(dst, b, h) do { _Pragma("unroll") for (int m = 0; m < 4; ++m) _Pragma("unroll") for (int k = 0; k < 2; ++k) dst[m][k] = *(const PG8_LAS bf16x8*)(lds + PG8_SA(b, h) + aoff + m * 2048 + k * 1024); } while (0)
; #define PG8_MMA(ai, bj, At, Bt) do { __builtin_amdgcn_s_setprio(1); _Pragma("unroll") for (int m = 0; m < 4; ++m) _Pragma("unroll") for (int n = 0; n < 2; ++n) _Pragma("unroll") for (int k = 0; k < 2; ++k) \
;         acc[ai][bj][m][n] = __builtin_amdgcn_mfma_f32_16x16x32_bf16(Bt[n][k], At[m][k], acc[ai][bj][m][n], 0, 0, 0); __builtin_amdgcn_s_setprio(0); } while (0)
; #define PG8_WAIT_V(n) asm volatile("s_waitcnt vmcnt(" #n ")" ::: "memory")
; #define PG8_WAIT_L(n) asm volatile("s_waitcnt lgkmcnt(" #n ")" ::: "memory")
; #define PG8_BAR __builtin_amdgcn_s_barrier()
; #define PG8_SCHED __builtin_amdgcn_sched_barrier(0)
; template <class Epi, class Sched, bool ALIGN_EPI = false, bool SP2 = false>
; __device__ __forceinline__ void gemm_phase(PG8_LAS unsigned char* lds, const Gemm g, const Sched& S, const Epi& E) {
;     ...
;             PG8_WAIT_V(8); PG8_WAIT_L(0); PG8_BAR; PG8_MMA(0, 0, At, B0); PG8_MMA(0, 1, At, B1); PG8_BAR; PG8_SCHED;
;             PG8_LDA(At, 1, 1); PG8_STAGE(PG8_SB(1, 0), b3, voffB); PG8_STAGE(PG8_SB(1, 1), b3 + hstep, voffB); PG8_STAGE(PG8_SA(1, 0), a3, voffA);
;             PG8_WAIT_V(8); PG8_WAIT_L(0); PG8_BAR; PG8_MMA(1, 0, At, B0); PG8_MMA(1, 1, At, B1); PG8_BAR; PG8_SCHED;
;     ...
;         if constexpr (ALIGN_EPI) { if (wr == 0) PG8_BAR; }
	v_mfma_f32_16x16x32_bf16 v[82:85], v[188:191], v[218:221], v[82:85]
	v_mfma_f32_16x16x32_bf16 v[70:73], v[180:183], v[226:229], v[70:73]
	v_mfma_f32_16x16x32_bf16 v[66:69], v[188:191], v[226:229], v[66:69]
	s_setprio 0
	s_add_u32 s62, s76, 0x8000
	s_addc_u32 s63, s77, 0
	s_add_i32 s59, s59, s3
	v_lshl_add_u64 v[158:159], s[62:63], 0, v[132:133]
	s_mov_b32 m0, s59
	ds_read_b128 v[198:201], v164 offset:49152
	ds_read_b128 v[202:205], v164 offset:50176
	ds_read_b128 v[206:209], v164 offset:51200
	ds_read_b128 v[210:213], v164 offset:52224
	ds_read_b128 v[214:217], v164 offset:53248
	ds_read_b128 v[218:221], v164 offset:54272
	ds_read_b128 v[222:225], v164 offset:55296
	ds_read_b128 v[226:229], v164 offset:56320
	global_load_lds_dwordx4 v[158:159], off
	s_add_i32 m0, s59, 0x2000
	v_lshl_add_u64 v[158:159], s[62:63], 0, v[136:137]
	s_add_u32 s62, s76, 0xc000
	s_addc_u32 s63, s77, 0
	s_add_i32 s59, s64, s3
	global_load_lds_dwordx4 v[158:159], off
	v_lshl_add_u64 v[158:159], s[62:63], 0, v[132:133]
	s_mov_b32 m0, s59
	s_nop 0
	global_load_lds_dwordx4 v[158:159], off
	v_lshl_add_u64 v[158:159], s[62:63], 0, v[136:137]
	s_add_i32 m0, s59, 0x2000
	s_nop 0
	global_load_lds_dwordx4 v[158:159], off
	s_waitcnt vmcnt(6)
	s_waitcnt lgkmcnt(0)
	s_barrier
	s_setprio 1
	s_waitcnt lgkmcnt(0)
	v_mfma_f32_16x16x32_bf16 v[62:65], v[146:149], v[198:201], v[62:65]
	v_mfma_f32_16x16x32_bf16 v[58:61], v[154:157], v[198:201], v[58:61]
	v_mfma_f32_16x16x32_bf16 v[46:49], v[146:149], v[206:209], v[46:49]
	v_mfma_f32_16x16x32_bf16 v[42:45], v[154:157], v[206:209], v[42:45]
	v_mfma_f32_16x16x32_bf16 v[30:33], v[146:149], v[214:217], v[30:33]
	v_mfma_f32_16x16x32_bf16 v[26:29], v[154:157], v[214:217], v[26:29]
	v_mfma_f32_16x16x32_bf16 v[14:17], v[146:149], v[222:225], v[14:17]
	v_mfma_f32_16x16x32_bf16 v[10:13], v[154:157], v[222:225], v[10:13]
	v_mfma_f32_16x16x32_bf16 v[62:65], v[150:153], v[202:205], v[62:65]
	v_mfma_f32_16x16x32_bf16 v[58:61], v[168:171], v[202:205], v[58:61]
	v_mfma_f32_16x16x32_bf16 v[46:49], v[150:153], v[210:213], v[46:49]
	v_mfma_f32_16x16x32_bf16 v[42:45], v[168:171], v[210:213], v[42:45]
	v_mfma_f32_16x16x32_bf16 v[30:33], v[150:153], v[218:221], v[30:33]
	v_mfma_f32_16x16x32_bf16 v[26:29], v[168:171], v[218:221], v[26:29]
	v_mfma_f32_16x16x32_bf16 v[14:17], v[150:153], v[226:229], v[14:17]
	v_mfma_f32_16x16x32_bf16 v[10:13], v[168:171], v[226:229], v[10:13]
	s_setprio 0
	s_setprio 1
	v_mfma_f32_16x16x32_bf16 v[54:57], v[172:175], v[198:201], v[54:57]
	v_mfma_f32_16x16x32_bf16 v[50:53], v[184:187], v[198:201], v[50:53]
	v_mfma_f32_16x16x32_bf16 v[38:41], v[172:175], v[206:209], v[38:41]
	v_mfma_f32_16x16x32_bf16 v[34:37], v[184:187], v[206:209], v[34:37]
	v_mfma_f32_16x16x32_bf16 v[22:25], v[172:175], v[214:217], v[22:25]
	v_mfma_f32_16x16x32_bf16 v[18:21], v[184:187], v[214:217], v[18:21]
	v_mfma_f32_16x16x32_bf16 v[6:9], v[172:175], v[222:225], v[6:9]
	v_mfma_f32_16x16x32_bf16 v[2:5], v[184:187], v[222:225], v[2:5]
	v_mfma_f32_16x16x32_bf16 v[54:57], v[180:183], v[202:205], v[54:57]
	v_mfma_f32_16x16x32_bf16 v[50:53], v[188:191], v[202:205], v[50:53]
	v_mfma_f32_16x16x32_bf16 v[38:41], v[180:183], v[210:213], v[38:41]
	v_mfma_f32_16x16x32_bf16 v[34:37], v[188:191], v[210:213], v[34:37]
	v_mfma_f32_16x16x32_bf16 v[22:25], v[180:183], v[218:221], v[22:25]
	s_setprio 2
	s_barrier
	v_mfma_f32_16x16x32_bf16 v[18:21], v[188:191], v[218:221], v[18:21]
	v_mfma_f32_16x16x32_bf16 v[6:9], v[180:183], v[226:229], v[6:9]
	v_mfma_f32_16x16x32_bf16 v[2:5], v[188:191], v[226:229], v[2:5]
	s_setprio 0
	s_add_i32 s58, s58, 2
	s_add_u32 s72, s72, 0x10000
	s_addc_u32 s73, s73, 0
	s_add_u32 s33, s33, 0x10000
	s_addc_u32 s56, s56, 0
	s_cmp_gt_u32 s58, 61
	s_cbranch_scc0 .LBB0_290
	s_and_b64 vcc, exec, s[12:13]
	s_cbranch_vccz .LBB0_293
	s_barrier

; #define PG8_STAGE(bufoff, gbase, voff) do { _Pragma("unroll") for (int _i = 0; _i < 2; ++_i) \
;         __builtin_amdgcn_global_load_lds((const unsigned*)((const char*)(gbase) + (voff)[_i]), (PG8_LAS unsigned*)(lds + (bufoff) + ldsw + _i * 8192), 16, 0, 0); } while (0)
; #define PG8_LDA(dst, b, h) do { _Pragma("unroll") for (int m = 0; m < 4; ++m) _Pragma("unroll") for (int k = 0; k < 2; ++k) dst[m][k] = *(const PG8_LAS bf16x8*)(lds + PG8_SA(b, h) + aoff + m * 2048 + k * 1024); } while (0)
; #define PG8_LDB(dst, b, h) do { _Pragma("unroll") for (int n = 0; n < 2; ++n) _Pragma("unroll") for (int k = 0; k < 2; ++k) dst[n][k] = *(const PG8_LAS bf16x8*)(lds + PG8_SB(b, h) + boff + n * 2048 + k * 1024); } while (0)
; #define PG8_MMA(ai, bj, At, Bt) do { __builtin_amdgcn_s_setprio(1); _Pragma("unroll") for (int m = 0; m < 4; ++m) _Pragma("unroll") for (int n = 0; n < 2; ++n) _Pragma("unroll") for (int k = 0; k < 2; ++k) \
;         acc[ai][bj][m][n] = __builtin_amdgcn_mfma_f32_16x16x32_bf16(Bt[n][k], At[m][k], acc[ai][bj][m][n], 0, 0, 0); __builtin_amdgcn_s_setprio(0); } while (0)
; #define PG8_WAIT_V(n) asm volatile("s_waitcnt vmcnt(" #n ")" ::: "memory")
; #define PG8_WAIT_L(n) asm volatile("s_waitcnt lgkmcnt(" #n ")" ::: "memory")
; template <class Epi, class Sched, bool ALIGN_EPI = false, bool SP2 = false>
; __device__ __forceinline__ void gemm_phase(PG8_LAS unsigned char* lds, const Gemm g, const Sched& S, const Epi& E) {
;     ...
;         for (; t < tend; t += 2) {
;             const bool last = (t == nt - 2);
;             const char* a1 = cA + (size_t)(t + 1) * kstep;
;             const char* a2 = last ? nA : cA + (size_t)(t + 2) * kstep; const char* b2 = last ? nB : cB + (size_t)(t + 2) * kstep;
;             const char* a3 = a2 + kstep; const char* b3 = b2 + kstep;
;             if (last && has_next) S.a_ready(nxt);
;             if constexpr (SP2) {
;             PG8_LDB(B0, 0, 0); PG8_LDB(B1, 0, 1); PG8_SCHED; PG8_LDA(At, 0, 0); PG8_STAGE(PG8_SA(1, 1), a1 + hstep, voffA);
;             PG8_WAIT_V(8); PG8_WAIT_L(0); PG8_BAR; PG8_MMA(0, 0, At, B0); PG8_MMA(0, 1, At, B1); PG8_BAR; PG8_SCHED;
;             PG8_LDA(At, 0, 1); PG8_STAGE(PG8_SB(0, 0), b2, voffB); PG8_STAGE(PG8_SB(0, 1), b2 + hstep, voffB); PG8_STAGE(PG8_SA(0, 0), a2, voffA);
;             PG8_WAIT_V(8); PG8_WAIT_L(0); PG8_BAR; PG8_MMA(1, 0, At, B0); PG8_MMA(1, 1, At, B1); PG8_BAR; PG8_SCHED;
.LBB0_757:
	ds_read_b128 v[154:157], v149
	ds_read_b128 v[158:161], v149 offset:1024
	ds_read_b128 v[162:165], v149 offset:2048
	ds_read_b128 v[166:169], v149 offset:3072
	ds_read_b128 v[170:173], v150
	ds_read_b128 v[174:177], v150 offset:1024
	ds_read_b128 v[180:183], v150 offset:2048
	ds_read_b128 v[184:187], v150 offset:3072
	s_add_u32 s46, s44, 0x4000
	s_addc_u32 s47, s45, 0
	s_cmp_eq_u32 s70, 60
	s_cselect_b32 s50, s39, s46
	s_cselect_b32 s51, s17, s47
	s_cselect_b32 s48, s41, s68
	s_cselect_b32 s49, s15, s69
	s_add_u32 s46, s50, 0x8000
	s_addc_u32 s47, s51, 0
	s_sub_u32 s46, s44, 0x4000
	s_subb_u32 s47, s45, 0
	v_lshl_add_u64 v[146:147], s[46:47], 0, v[130:131]
	s_mov_b32 m0, s57
	s_nop 0
	global_load_lds_dwordx4 v[146:147], off
	v_lshl_add_u64 v[146:147], s[46:47], 0, v[134:135]
	s_mov_b32 m0, s58
	s_nop 0
	global_load_lds_dwordx4 v[146:147], off
	v_lshl_add_u64 v[146:147], s[44:45], 0, v[138:139]
	s_add_i32 m0, s26, 0xc000
	ds_read_b128 v[188:191], v151
	ds_read_b128 v[198:201], v151 offset:1024
	ds_read_b128 v[202:205], v151 offset:2048
	ds_read_b128 v[206:209], v151 offset:3072
	ds_read_b128 v[210:213], v151 offset:4096
	ds_read_b128 v[214:217], v151 offset:5120
	ds_read_b128 v[218:221], v151 offset:6144
	ds_read_b128 v[222:225], v151 offset:7168
	global_load_lds_dwordx4 v[146:147], off
	v_lshl_add_u64 v[146:147], s[44:45], 0, v[140:141]
	s_add_i32 m0, s26, 0xe000
	s_nop 0
	global_load_lds_dwordx4 v[146:147], off
	s_waitcnt vmcnt(8)
	s_waitcnt lgkmcnt(0)
	s_barrier
	s_setprio 1
	s_waitcnt lgkmcnt(0)
	v_mfma_f32_16x16x32_bf16 v[126:129], v[154:157], v[188:191], v[126:129]
	v_mfma_f32_16x16x32_bf16 v[122:125], v[162:165], v[188:191], v[122:125]
	v_mfma_f32_16x16x32_bf16 v[110:113], v[154:157], v[202:205], v[110:113]
	v_mfma_f32_16x16x32_bf16 v[106:109], v[162:165], v[202:205], v[106:109]
	v_mfma_f32_16x16x32_bf16 v[94:97], v[154:157], v[210:213], v[94:97]
	v_mfma_f32_16x16x32_bf16 v[90:93], v[162:165], v[210:213], v[90:93]
	v_mfma_f32_16x16x32_bf16 v[78:81], v[154:157], v[218:221], v[78:81]
	v_mfma_f32_16x16x32_bf16 v[74:77], v[162:165], v[218:221], v[74:77]
	v_mfma_f32_16x16x32_bf16 v[126:129], v[158:161], v[198:201], v[126:129]
	v_mfma_f32_16x16x32_bf16 v[122:125], v[166:169], v[198:201], v[122:125]
	v_mfma_f32_16x16x32_bf16 v[110:113], v[158:161], v[206:209], v[110:113]
	v_mfma_f32_16x16x32_bf16 v[106:109], v[166:169], v[206:209], v[106:109]
	v_mfma_f32_16x16x32_bf16 v[94:97], v[158:161], v[214:217], v[94:97]
	v_mfma_f32_16x16x32_bf16 v[90:93], v[166:169], v[214:217], v[90:93]
	v_mfma_f32_16x16x32_bf16 v[78:81], v[158:161], v[222:225], v[78:81]
	v_mfma_f32_16x16x32_bf16 v[74:77], v[166:169], v[222:225], v[74:77]
	s_setprio 0
	s_setprio 1
	v_mfma_f32_16x16x32_bf16 v[118:121], v[170:173], v[188:191], v[118:121]
	v_mfma_f32_16x16x32_bf16 v[114:117], v[180:183], v[188:191], v[114:117]
	v_mfma_f32_16x16x32_bf16 v[102:105], v[170:173], v[202:205], v[102:105]
	v_mfma_f32_16x16x32_bf16 v[98:101], v[180:183], v[202:205], v[98:101]
	v_mfma_f32_16x16x32_bf16 v[86:89], v[170:173], v[210:213], v[86:89]
	v_mfma_f32_16x16x32_bf16 v[82:85], v[180:183], v[210:213], v[82:85]
	v_mfma_f32_16x16x32_bf16 v[70:73], v[170:173], v[218:221], v[70:73]
	v_mfma_f32_16x16x32_bf16 v[66:69], v[180:183], v[218:221], v[66:69]
	v_mfma_f32_16x16x32_bf16 v[118:121], v[174:177], v[198:201], v[118:121]
	v_mfma_f32_16x16x32_bf16 v[114:117], v[184:187], v[198:201], v[114:117]
	v_mfma_f32_16x16x32_bf16 v[102:105], v[174:177], v[206:209], v[102:105]
	v_mfma_f32_16x16x32_bf16 v[98:101], v[184:187], v[206:209], v[98:101]
	v_mfma_f32_16x16x32_bf16 v[86:89], v[174:177], v[214:217], v[86:89]
	s_setprio 2
	s_barrier
	v_mfma_f32_16x16x32_bf16 v[82:85], v[184:187], v[214:217], v[82:85]
	v_mfma_f32_16x16x32_bf16 v[70:73], v[174:177], v[222:225], v[70:73]
	v_mfma_f32_16x16x32_bf16 v[66:69], v[184:187], v[222:225], v[66:69]
	s_setprio 0
	s_add_i32 s71, s59, s3
	v_lshl_add_u64 v[146:147], s[48:49], 0, v[132:133]
	s_mov_b32 m0, s71
	ds_read_b128 v[188:191], v151 offset:16384
	ds_read_b128 v[198:201], v151 offset:17408
	ds_read_b128 v[202:205], v151 offset:18432
	ds_read_b128 v[206:209], v151 offset:19456
	ds_read_b128 v[210:213], v151 offset:20480
	ds_read_b128 v[214:217], v151 offset:21504
	ds_read_b128 v[218:221], v151 offset:22528
	ds_read_b128 v[222:225], v151 offset:23552
	global_load_lds_dwordx4 v[146:147], off
	s_add_i32 m0, s71, 0x2000
	s_add_u32 s72, s48, 0x4000
	v_lshl_add_u64 v[146:147], s[48:49], 0, v[136:137]
	s_addc_u32 s73, s49, 0
	s_add_i32 s71, s61, s3
	global_load_lds_dwordx4 v[146:147], off
	v_lshl_add_u64 v[146:147], s[72:73], 0, v[132:133]
	s_mov_b32 m0, s71
	s_nop 0
	global_load_lds_dwordx4 v[146:147], off
	v_lshl_add_u64 v[146:147], s[72:73], 0, v[136:137]
	s_add_i32 m0, s71, 0x2000
	s_nop 0
	global_load_lds_dwordx4 v[146:147], off
	s_waitcnt vmcnt(6)
	s_waitcnt lgkmcnt(0)
	s_barrier
; #define PG8_STAGE(bufoff, gbase, voff) do { _Pragma("unroll") for (int _i = 0; _i < 2; ++_i) \
;         __builtin_amdgcn_global_load_lds((const unsigned*)((const char*)(gbase) + (voff)[_i]), (PG8_LAS unsigned*)(lds + (bufoff) + ldsw + _i * 8192), 16, 0, 0); } while (0)
; #define PG8_LDA(dst, b, h) do { _Pragma("unroll") for (int m = 0; m < 4; ++m) _Pragma("unroll") for (int k = 0; k < 2; ++k) dst[m][k] = *(const PG8_LAS bf16x8*)(lds + PG8_SA(b, h) + aoff + m * 2048 + k * 1024); } while (0)
; #define PG8_LDB(dst, b, h) do { _Pragma("unroll") for (int n = 0; n < 2; ++n) _Pragma("unroll") for (int k = 0; k < 2; ++k) dst[n][k] = *(const PG8_LAS bf16x8*)(lds + PG8_SB(b, h) + boff + n * 2048 + k * 1024); } while (0)
; #define PG8_MMA(ai, bj, At, Bt) do { __builtin_amdgcn_s_setprio(1); _Pragma("unroll") for (int m = 0; m < 4; ++m) _Pragma("unroll") for (int n = 0; n < 2; ++n) _Pragma("unroll") for (int k = 0; k < 2; ++k) \
;         acc[ai][bj][m][n] = __builtin_amdgcn_mfma_f32_16x16x32_bf16(Bt[n][k], At[m][k], acc[ai][bj][m][n], 0, 0, 0); __builtin_amdgcn_s_setprio(0); } while (0)
; #define PG8_WAIT_V(n) asm volatile("s_waitcnt vmcnt(" #n ")" ::: "memory")
; #define PG8_WAIT_L(n) asm volatile("s_waitcnt lgkmcnt(" #n ")" ::: "memory")
; #define PG8_BAR __builtin_amdgcn_s_barrier()
; #define PG8_SCHED __builtin_amdgcn_sched_barrier(0)
; template <class Epi, class Sched, bool ALIGN_EPI = false, bool SP2 = false>
; __device__ __forceinline__ void gemm_phase(PG8_LAS unsigned char* lds, const Gemm g, const Sched& S, const Epi& E) {
;     ...
;             PG8_WAIT_V(8); PG8_WAIT_L(0); PG8_BAR; PG8_MMA(1, 0, At, B0); PG8_MMA(1, 1, At, B1); PG8_BAR; PG8_SCHED;
;             PG8_LDB(B0, 1, 0); PG8_LDB(B1, 1, 1); PG8_SCHED; PG8_LDA(At, 1, 0); PG8_STAGE(PG8_SA(0, 1), a2 + hstep, voffA);
;             PG8_WAIT_V(8); PG8_WAIT_L(0); PG8_BAR; PG8_MMA(0, 0, At, B0); PG8_MMA(0, 1, At, B1); PG8_BAR; PG8_SCHED;
;             PG8_LDA(At, 1, 1); PG8_STAGE(PG8_SB(1, 0), b3, voffB); PG8_STAGE(PG8_SB(1, 1), b3 + hstep, voffB); PG8_STAGE(PG8_SA(1, 0), a3, voffA);
;             PG8_WAIT_V(8); PG8_WAIT_L(0); PG8_BAR; PG8_MMA(1, 0, At, B0); PG8_MMA(1, 1, At, B1); PG8_BAR; PG8_SCHED;
	s_setprio 1
	s_waitcnt lgkmcnt(0)
	v_mfma_f32_16x16x32_bf16 v[62:65], v[154:157], v[188:191], v[62:65]
	v_mfma_f32_16x16x32_bf16 v[58:61], v[162:165], v[188:191], v[58:61]
	v_mfma_f32_16x16x32_bf16 v[46:49], v[154:157], v[202:205], v[46:49]
	v_mfma_f32_16x16x32_bf16 v[42:45], v[162:165], v[202:205], v[42:45]
	v_mfma_f32_16x16x32_bf16 v[30:33], v[154:157], v[210:213], v[30:33]
	v_mfma_f32_16x16x32_bf16 v[26:29], v[162:165], v[210:213], v[26:29]
	v_mfma_f32_16x16x32_bf16 v[14:17], v[154:157], v[218:221], v[14:17]
	v_mfma_f32_16x16x32_bf16 v[10:13], v[162:165], v[218:221], v[10:13]
	v_mfma_f32_16x16x32_bf16 v[62:65], v[158:161], v[198:201], v[62:65]
	v_mfma_f32_16x16x32_bf16 v[58:61], v[166:169], v[198:201], v[58:61]
	v_mfma_f32_16x16x32_bf16 v[46:49], v[158:161], v[206:209], v[46:49]
	v_mfma_f32_16x16x32_bf16 v[42:45], v[166:169], v[206:209], v[42:45]
	v_mfma_f32_16x16x32_bf16 v[30:33], v[158:161], v[214:217], v[30:33]
	v_mfma_f32_16x16x32_bf16 v[26:29], v[166:169], v[214:217], v[26:29]
	v_mfma_f32_16x16x32_bf16 v[14:17], v[158:161], v[222:225], v[14:17]
	v_mfma_f32_16x16x32_bf16 v[10:13], v[166:169], v[222:225], v[10:13]
	s_setprio 0
	s_setprio 1
	v_mfma_f32_16x16x32_bf16 v[54:57], v[170:173], v[188:191], v[54:57]
	v_mfma_f32_16x16x32_bf16 v[50:53], v[180:183], v[188:191], v[50:53]
	v_mfma_f32_16x16x32_bf16 v[38:41], v[170:173], v[202:205], v[38:41]
	v_mfma_f32_16x16x32_bf16 v[34:37], v[180:183], v[202:205], v[34:37]
	v_mfma_f32_16x16x32_bf16 v[22:25], v[170:173], v[210:213], v[22:25]
	v_mfma_f32_16x16x32_bf16 v[18:21], v[180:183], v[210:213], v[18:21]
	v_mfma_f32_16x16x32_bf16 v[6:9], v[170:173], v[218:221], v[6:9]
	v_mfma_f32_16x16x32_bf16 v[2:5], v[180:183], v[218:221], v[2:5]
	v_mfma_f32_16x16x32_bf16 v[54:57], v[174:177], v[198:201], v[54:57]
	v_mfma_f32_16x16x32_bf16 v[50:53], v[184:187], v[198:201], v[50:53]
	v_mfma_f32_16x16x32_bf16 v[38:41], v[174:177], v[206:209], v[38:41]
	v_mfma_f32_16x16x32_bf16 v[34:37], v[184:187], v[206:209], v[34:37]
	v_mfma_f32_16x16x32_bf16 v[22:25], v[174:177], v[214:217], v[22:25]
	s_setprio 2
	s_barrier
	v_mfma_f32_16x16x32_bf16 v[18:21], v[184:187], v[214:217], v[18:21]
	v_mfma_f32_16x16x32_bf16 v[6:9], v[174:177], v[222:225], v[6:9]
	v_mfma_f32_16x16x32_bf16 v[2:5], v[184:187], v[222:225], v[2:5]
	s_setprio 0
	s_add_i32 s71, 0, 0x18000
	v_add_u32_e32 v146, s71, v1
	s_add_i32 s72, 0, 0x1c000
	ds_read_b128 v[154:157], v146
	ds_read_b128 v[158:161], v146 offset:1024
	ds_read_b128 v[162:165], v146 offset:2048
	ds_read_b128 v[166:169], v146 offset:3072
	v_add_u32_e32 v146, s72, v1
	ds_read_b128 v[170:173], v146
	ds_read_b128 v[174:177], v146 offset:1024
	ds_read_b128 v[180:183], v146 offset:2048
	ds_read_b128 v[184:187], v146 offset:3072
	v_lshl_add_u64 v[146:147], s[50:51], 0, v[130:131]
	s_mov_b32 m0, s26
	s_nop 0
	global_load_lds_dwordx4 v[146:147], off
	v_lshl_add_u64 v[146:147], s[50:51], 0, v[134:135]
	s_mov_b32 m0, s27
	s_nop 0
	global_load_lds_dwordx4 v[146:147], off
	s_add_u32 s50, s50, 0x4000
	s_addc_u32 s51, s51, 0
	s_mov_b32 m0, s28
	v_lshl_add_u64 v[146:147], s[50:51], 0, v[130:131]
	ds_read_b128 v[188:191], v151 offset:32768
	ds_read_b128 v[198:201], v151 offset:33792
	ds_read_b128 v[202:205], v151 offset:34816
	ds_read_b128 v[206:209], v151 offset:35840
	ds_read_b128 v[210:213], v151 offset:36864
	ds_read_b128 v[214:217], v151 offset:37888
	ds_read_b128 v[218:221], v151 offset:38912
	ds_read_b128 v[222:225], v151 offset:39936
	global_load_lds_dwordx4 v[146:147], off
	v_lshl_add_u64 v[146:147], s[50:51], 0, v[134:135]
	s_mov_b32 m0, s29
	s_nop 0
	global_load_lds_dwordx4 v[146:147], off
	s_waitcnt vmcnt(8)
	s_waitcnt lgkmcnt(0)
	s_barrier
	s_setprio 1
	s_waitcnt lgkmcnt(0)
	v_mfma_f32_16x16x32_bf16 v[126:129], v[154:157], v[188:191], v[126:129]
	v_mfma_f32_16x16x32_bf16 v[122:125], v[162:165], v[188:191], v[122:125]
	v_mfma_f32_16x16x32_bf16 v[110:113], v[154:157], v[202:205], v[110:113]
	v_mfma_f32_16x16x32_bf16 v[106:109], v[162:165], v[202:205], v[106:109]
	v_mfma_f32_16x16x32_bf16 v[94:97], v[154:157], v[210:213], v[94:97]
	v_mfma_f32_16x16x32_bf16 v[90:93], v[162:165], v[210:213], v[90:93]
	v_mfma_f32_16x16x32_bf16 v[78:81], v[154:157], v[218:221], v[78:81]
	v_mfma_f32_16x16x32_bf16 v[74:77], v[162:165], v[218:221], v[74:77]
	v_mfma_f32_16x16x32_bf16 v[126:129], v[158:161], v[198:201], v[126:129]
	v_mfma_f32_16x16x32_bf16 v[122:125], v[166:169], v[198:201], v[122:125]
	v_mfma_f32_16x16x32_bf16 v[110:113], v[158:161], v[206:209], v[110:113]
	v_mfma_f32_16x16x32_bf16 v[106:109], v[166:169], v[206:209], v[106:109]
	v_mfma_f32_16x16x32_bf16 v[94:97], v[158:161], v[214:217], v[94:97]
	v_mfma_f32_16x16x32_bf16 v[90:93], v[166:169], v[214:217], v[90:93]
	v_mfma_f32_16x16x32_bf16 v[78:81], v[158:161], v[222:225], v[78:81]
	v_mfma_f32_16x16x32_bf16 v[74:77], v[166:169], v[222:225], v[74:77]
	s_setprio 0
	s_setprio 1
	v_mfma_f32_16x16x32_bf16 v[118:121], v[170:173], v[188:191], v[118:121]
	v_mfma_f32_16x16x32_bf16 v[114:117], v[180:183], v[188:191], v[114:117]
	v_mfma_f32_16x16x32_bf16 v[102:105], v[170:173], v[202:205], v[102:105]
	v_mfma_f32_16x16x32_bf16 v[98:101], v[180:183], v[202:205], v[98:101]
	v_mfma_f32_16x16x32_bf16 v[86:89], v[170:173], v[210:213], v[86:89]
	v_mfma_f32_16x16x32_bf16 v[82:85], v[180:183], v[210:213], v[82:85]
	v_mfma_f32_16x16x32_bf16 v[70:73], v[170:173], v[218:221], v[70:73]
	v_mfma_f32_16x16x32_bf16 v[66:69], v[180:183], v[218:221], v[66:69]
	v_mfma_f32_16x16x32_bf16 v[118:121], v[174:177], v[198:201], v[118:121]
	v_mfma_f32_16x16x32_bf16 v[114:117], v[184:187], v[198:201], v[114:117]
	v_mfma_f32_16x16x32_bf16 v[102:105], v[174:177], v[206:209], v[102:105]
	v_mfma_f32_16x16x32_bf16 v[98:101], v[184:187], v[206:209], v[98:101]
	v_mfma_f32_16x16x32_bf16 v[86:89], v[174:177], v[214:217], v[86:89]
	s_setprio 2
	s_barrier
; #define PG8_STAGE(bufoff, gbase, voff) do { _Pragma("unroll") for (int _i = 0; _i < 2; ++_i) \
;         __builtin_amdgcn_global_load_lds((const unsigned*)((const char*)(gbase) + (voff)[_i]), (PG8_LAS unsigned*)(lds + (bufoff) + ldsw + _i * 8192), 16, 0, 0); } while (0)
; #define PG8_LDA(dst, b, h) do { _Pragma("unroll") for (int m = 0; m < 4; ++m) _Pragma("unroll") for (int k = 0; k < 2; ++k) dst[m][k] = *(const PG8_LAS bf16x8*)(lds + PG8_SA(b, h) + aoff + m * 2048 + k * 1024); } while (0)
; #define PG8_MMA(ai, bj, At, Bt) do { __builtin_amdgcn_s_setprio(1); _Pragma("unroll") for (int m = 0; m < 4; ++m) _Pragma("unroll") for (int n = 0; n < 2; ++n) _Pragma("unroll") for (int k = 0; k < 2; ++k) \
;         acc[ai][bj][m][n] = __builtin_amdgcn_mfma_f32_16x16x32_bf16(Bt[n][k], At[m][k], acc[ai][bj][m][n], 0, 0, 0); __builtin_amdgcn_s_setprio(0); } while (0)
; #define PG8_WAIT_V(n) asm volatile("s_waitcnt vmcnt(" #n ")" ::: "memory")
; #define PG8_WAIT_L(n) asm volatile("s_waitcnt lgkmcnt(" #n ")" ::: "memory")
; #define PG8_BAR __builtin_amdgcn_s_barrier()
; #define PG8_SCHED __builtin_amdgcn_sched_barrier(0)
; template <class Epi, class Sched, bool ALIGN_EPI = false, bool SP2 = false>
; __device__ __forceinline__ void gemm_phase(PG8_LAS unsigned char* lds, const Gemm g, const Sched& S, const Epi& E) {
;     ...
;             PG8_WAIT_V(8); PG8_WAIT_L(0); PG8_BAR; PG8_MMA(0, 0, At, B0); PG8_MMA(0, 1, At, B1); PG8_BAR; PG8_SCHED;
;             PG8_LDA(At, 1, 1); PG8_STAGE(PG8_SB(1, 0), b3, voffB); PG8_STAGE(PG8_SB(1, 1), b3 + hstep, voffB); PG8_STAGE(PG8_SA(1, 0), a3, voffA);
;             PG8_WAIT_V(8); PG8_WAIT_L(0); PG8_BAR; PG8_MMA(1, 0, At, B0); PG8_MMA(1, 1, At, B1); PG8_BAR; PG8_SCHED;
;     ...
;         if constexpr (ALIGN_EPI) { if (wr == 0) PG8_BAR; }
	v_mfma_f32_16x16x32_bf16 v[82:85], v[184:187], v[214:217], v[82:85]
	v_mfma_f32_16x16x32_bf16 v[70:73], v[174:177], v[222:225], v[70:73]
	v_mfma_f32_16x16x32_bf16 v[66:69], v[184:187], v[222:225], v[66:69]
	s_setprio 0
	s_add_u32 s50, s48, 0x8000
	s_addc_u32 s51, s49, 0
	s_add_i32 s71, s71, s3
	v_lshl_add_u64 v[146:147], s[50:51], 0, v[132:133]
	s_mov_b32 m0, s71
	ds_read_b128 v[188:191], v151 offset:49152
	ds_read_b128 v[198:201], v151 offset:50176
	ds_read_b128 v[202:205], v151 offset:51200
	ds_read_b128 v[206:209], v151 offset:52224
	ds_read_b128 v[210:213], v151 offset:53248
	ds_read_b128 v[214:217], v151 offset:54272
	ds_read_b128 v[218:221], v151 offset:55296
	ds_read_b128 v[222:225], v151 offset:56320
	global_load_lds_dwordx4 v[146:147], off
	s_add_i32 m0, s71, 0x2000
	s_add_u32 s48, s48, 0xc000
	v_lshl_add_u64 v[146:147], s[50:51], 0, v[136:137]
	s_addc_u32 s49, s49, 0
	s_add_i32 s50, s72, s3
	global_load_lds_dwordx4 v[146:147], off
	v_lshl_add_u64 v[146:147], s[48:49], 0, v[132:133]
	s_mov_b32 m0, s50
	s_nop 0
	global_load_lds_dwordx4 v[146:147], off
	v_lshl_add_u64 v[146:147], s[48:49], 0, v[136:137]
	s_add_i32 m0, s50, 0x2000
	s_nop 0
	global_load_lds_dwordx4 v[146:147], off
	s_waitcnt vmcnt(6)
	s_waitcnt lgkmcnt(0)
	s_barrier
	s_setprio 1
	s_waitcnt lgkmcnt(0)
	v_mfma_f32_16x16x32_bf16 v[62:65], v[154:157], v[188:191], v[62:65]
	v_mfma_f32_16x16x32_bf16 v[58:61], v[162:165], v[188:191], v[58:61]
	v_mfma_f32_16x16x32_bf16 v[46:49], v[154:157], v[202:205], v[46:49]
	v_mfma_f32_16x16x32_bf16 v[42:45], v[162:165], v[202:205], v[42:45]
	v_mfma_f32_16x16x32_bf16 v[30:33], v[154:157], v[210:213], v[30:33]
	v_mfma_f32_16x16x32_bf16 v[26:29], v[162:165], v[210:213], v[26:29]
	v_mfma_f32_16x16x32_bf16 v[14:17], v[154:157], v[218:221], v[14:17]
	v_mfma_f32_16x16x32_bf16 v[10:13], v[162:165], v[218:221], v[10:13]
	v_mfma_f32_16x16x32_bf16 v[62:65], v[158:161], v[198:201], v[62:65]
	v_mfma_f32_16x16x32_bf16 v[58:61], v[166:169], v[198:201], v[58:61]
	v_mfma_f32_16x16x32_bf16 v[46:49], v[158:161], v[206:209], v[46:49]
	v_mfma_f32_16x16x32_bf16 v[42:45], v[166:169], v[206:209], v[42:45]
	v_mfma_f32_16x16x32_bf16 v[30:33], v[158:161], v[214:217], v[30:33]
	v_mfma_f32_16x16x32_bf16 v[26:29], v[166:169], v[214:217], v[26:29]
	v_mfma_f32_16x16x32_bf16 v[14:17], v[158:161], v[222:225], v[14:17]
	v_mfma_f32_16x16x32_bf16 v[10:13], v[166:169], v[222:225], v[10:13]
	s_setprio 0
	s_setprio 1
	v_mfma_f32_16x16x32_bf16 v[54:57], v[170:173], v[188:191], v[54:57]
	v_mfma_f32_16x16x32_bf16 v[50:53], v[180:183], v[188:191], v[50:53]
	v_mfma_f32_16x16x32_bf16 v[38:41], v[170:173], v[202:205], v[38:41]
	v_mfma_f32_16x16x32_bf16 v[34:37], v[180:183], v[202:205], v[34:37]
	v_mfma_f32_16x16x32_bf16 v[22:25], v[170:173], v[210:213], v[22:25]
	v_mfma_f32_16x16x32_bf16 v[18:21], v[180:183], v[210:213], v[18:21]
	v_mfma_f32_16x16x32_bf16 v[6:9], v[170:173], v[218:221], v[6:9]
	v_mfma_f32_16x16x32_bf16 v[2:5], v[180:183], v[218:221], v[2:5]
	v_mfma_f32_16x16x32_bf16 v[54:57], v[174:177], v[198:201], v[54:57]
	v_mfma_f32_16x16x32_bf16 v[50:53], v[184:187], v[198:201], v[50:53]
	v_mfma_f32_16x16x32_bf16 v[38:41], v[174:177], v[206:209], v[38:41]
	v_mfma_f32_16x16x32_bf16 v[34:37], v[184:187], v[206:209], v[34:37]
	v_mfma_f32_16x16x32_bf16 v[22:25], v[174:177], v[214:217], v[22:25]
	s_setprio 2
	s_barrier
	v_mfma_f32_16x16x32_bf16 v[18:21], v[184:187], v[214:217], v[18:21]
	v_mfma_f32_16x16x32_bf16 v[6:9], v[174:177], v[222:225], v[6:9]
	v_mfma_f32_16x16x32_bf16 v[2:5], v[184:187], v[222:225], v[2:5]
	s_setprio 0
	s_add_i32 s70, s70, 2
	s_add_u32 s44, s44, 0x10000
	s_addc_u32 s45, s45, 0
	s_add_u32 s68, s68, 0x10000
	s_addc_u32 s69, s69, 0
	s_cmp_gt_u32 s70, 61
	s_cbranch_scc0 .LBB0_757
	s_and_b64 vcc, exec, s[12:13]
	s_cbranch_vccz .LBB0_760
	s_barrier

; #define PG8_STAGE(bufoff, gbase, voff) do { _Pragma("unroll") for (int _i = 0; _i < 2; ++_i) \
;         __builtin_amdgcn_global_load_lds((const unsigned*)((const char*)(gbase) + (voff)[_i]), (PG8_LAS unsigned*)(lds + (bufoff) + ldsw + _i * 8192), 16, 0, 0); } while (0)
; #define PG8_LDA(dst, b, h) do { _Pragma("unroll") for (int m = 0; m < 4; ++m) _Pragma("unroll") for (int k = 0; k < 2; ++k) dst[m][k] = *(const PG8_LAS bf16x8*)(lds + PG8_SA(b, h) + aoff + m * 2048 + k * 1024); } while (0)
; #define PG8_LDB(dst, b, h) do { _Pragma("unroll") for (int n = 0; n < 2; ++n) _Pragma("unroll") for (int k = 0; k < 2; ++k) dst[n][k] = *(const PG8_LAS bf16x8*)(lds + PG8_SB(b, h) + boff + n * 2048 + k * 1024); } while (0)
; #define PG8_MMA(ai, bj, At, Bt) do { __builtin_amdgcn_s_setprio(1); _Pragma("unroll") for (int m = 0; m < 4; ++m) _Pragma("unroll") for (int n = 0; n < 2; ++n) _Pragma("unroll") for (int k = 0; k < 2; ++k) \
;         acc[ai][bj][m][n] = __builtin_amdgcn_mfma_f32_16x16x32_bf16(Bt[n][k], At[m][k], acc[ai][bj][m][n], 0, 0, 0); __builtin_amdgcn_s_setprio(0); } while (0)
; #define PG8_WAIT_V(n) asm volatile("s_waitcnt vmcnt(" #n ")" ::: "memory")
; #define PG8_WAIT_L(n) asm volatile("s_waitcnt lgkmcnt(" #n ")" ::: "memory")
; template <class Epi, class Sched, bool ALIGN_EPI = false, bool SP2 = false>
; __device__ __forceinline__ void gemm_phase(PG8_LAS unsigned char* lds, const Gemm g, const Sched& S, const Epi& E) {
;     ...
;         for (; t < tend; t += 2) {
;             const bool last = (t == nt - 2);
;             const char* a1 = cA + (size_t)(t + 1) * kstep;
;             const char* a2 = last ? nA : cA + (size_t)(t + 2) * kstep; const char* b2 = last ? nB : cB + (size_t)(t + 2) * kstep;
;             const char* a3 = a2 + kstep; const char* b3 = b2 + kstep;
;             if (last && has_next) S.a_ready(nxt);
;             if constexpr (SP2) {
;             PG8_LDB(B0, 0, 0); PG8_LDB(B1, 0, 1); PG8_SCHED; PG8_LDA(At, 0, 0); PG8_STAGE(PG8_SA(1, 1), a1 + hstep, voffA);
;             PG8_WAIT_V(8); PG8_WAIT_L(0); PG8_BAR; PG8_MMA(0, 0, At, B0); PG8_MMA(0, 1, At, B1); PG8_BAR; PG8_SCHED;
;             PG8_LDA(At, 0, 1); PG8_STAGE(PG8_SB(0, 0), b2, voffB); PG8_STAGE(PG8_SB(0, 1), b2 + hstep, voffB); PG8_STAGE(PG8_SA(0, 0), a2, voffA);
;             PG8_WAIT_V(8); PG8_WAIT_L(0); PG8_BAR; PG8_MMA(1, 0, At, B0); PG8_MMA(1, 1, At, B1); PG8_BAR; PG8_SCHED;
.LBB0_840:
	ds_read_b128 v[148:151], v153
	ds_read_b128 v[158:161], v153 offset:1024
	ds_read_b128 v[162:165], v153 offset:2048
	ds_read_b128 v[166:169], v153 offset:3072
	ds_read_b128 v[170:173], v154
	ds_read_b128 v[174:177], v154 offset:1024
	ds_read_b128 v[180:183], v154 offset:2048
	ds_read_b128 v[184:187], v154 offset:3072
	s_add_u32 s42, s40, 0x4000
	s_addc_u32 s43, s41, 0
	s_cmp_eq_u32 s69, 60
	s_cselect_b32 s46, s65, s42
	s_cselect_b32 s47, s23, s43
	s_cselect_b32 s44, s66, s67
	s_cselect_b32 s45, s17, s68
	s_add_u32 s42, s46, 0x8000
	s_addc_u32 s43, s47, 0
	s_sub_u32 s42, s40, 0x4000
	s_subb_u32 s43, s41, 0
	v_lshl_add_u64 v[226:227], s[42:43], 0, v[130:131]
	s_mov_b32 m0, s50
	s_nop 0
	global_load_lds_dwordx4 v[226:227], off
	v_lshl_add_u64 v[226:227], s[42:43], 0, v[134:135]
	s_mov_b32 m0, s51
	s_nop 0
	global_load_lds_dwordx4 v[226:227], off
	v_lshl_add_u64 v[226:227], s[40:41], 0, v[140:141]
	s_add_i32 m0, s28, 0xc000
	ds_read_b128 v[188:191], v155
	ds_read_b128 v[198:201], v155 offset:1024
	ds_read_b128 v[202:205], v155 offset:2048
	ds_read_b128 v[206:209], v155 offset:3072
	ds_read_b128 v[210:213], v155 offset:4096
	ds_read_b128 v[214:217], v155 offset:5120
	ds_read_b128 v[218:221], v155 offset:6144
	ds_read_b128 v[222:225], v155 offset:7168
	global_load_lds_dwordx4 v[226:227], off
	v_lshl_add_u64 v[226:227], s[40:41], 0, v[142:143]
	s_add_i32 m0, s28, 0xe000
	s_nop 0
	global_load_lds_dwordx4 v[226:227], off
	s_waitcnt vmcnt(8)
	s_waitcnt lgkmcnt(0)
	s_barrier
	s_setprio 1
	s_waitcnt lgkmcnt(0)
	v_mfma_f32_16x16x32_bf16 v[126:129], v[148:151], v[188:191], v[126:129]
	v_mfma_f32_16x16x32_bf16 v[122:125], v[162:165], v[188:191], v[122:125]
	v_mfma_f32_16x16x32_bf16 v[110:113], v[148:151], v[202:205], v[110:113]
	v_mfma_f32_16x16x32_bf16 v[106:109], v[162:165], v[202:205], v[106:109]
	v_mfma_f32_16x16x32_bf16 v[94:97], v[148:151], v[210:213], v[94:97]
	v_mfma_f32_16x16x32_bf16 v[90:93], v[162:165], v[210:213], v[90:93]
	v_mfma_f32_16x16x32_bf16 v[78:81], v[148:151], v[218:221], v[78:81]
	v_mfma_f32_16x16x32_bf16 v[74:77], v[162:165], v[218:221], v[74:77]
	v_mfma_f32_16x16x32_bf16 v[126:129], v[158:161], v[198:201], v[126:129]
	v_mfma_f32_16x16x32_bf16 v[122:125], v[166:169], v[198:201], v[122:125]
	v_mfma_f32_16x16x32_bf16 v[110:113], v[158:161], v[206:209], v[110:113]
	v_mfma_f32_16x16x32_bf16 v[106:109], v[166:169], v[206:209], v[106:109]
	v_mfma_f32_16x16x32_bf16 v[94:97], v[158:161], v[214:217], v[94:97]
	v_mfma_f32_16x16x32_bf16 v[90:93], v[166:169], v[214:217], v[90:93]
	v_mfma_f32_16x16x32_bf16 v[78:81], v[158:161], v[222:225], v[78:81]
	v_mfma_f32_16x16x32_bf16 v[74:77], v[166:169], v[222:225], v[74:77]
	s_setprio 0
	s_setprio 1
	v_mfma_f32_16x16x32_bf16 v[118:121], v[170:173], v[188:191], v[118:121]
	v_mfma_f32_16x16x32_bf16 v[114:117], v[180:183], v[188:191], v[114:117]
	v_mfma_f32_16x16x32_bf16 v[102:105], v[170:173], v[202:205], v[102:105]
	v_mfma_f32_16x16x32_bf16 v[98:101], v[180:183], v[202:205], v[98:101]
	v_mfma_f32_16x16x32_bf16 v[86:89], v[170:173], v[210:213], v[86:89]
	v_mfma_f32_16x16x32_bf16 v[82:85], v[180:183], v[210:213], v[82:85]
	v_mfma_f32_16x16x32_bf16 v[70:73], v[170:173], v[218:221], v[70:73]
	v_mfma_f32_16x16x32_bf16 v[66:69], v[180:183], v[218:221], v[66:69]
	v_mfma_f32_16x16x32_bf16 v[118:121], v[174:177], v[198:201], v[118:121]
	v_mfma_f32_16x16x32_bf16 v[114:117], v[184:187], v[198:201], v[114:117]
	v_mfma_f32_16x16x32_bf16 v[102:105], v[174:177], v[206:209], v[102:105]
	v_mfma_f32_16x16x32_bf16 v[98:101], v[184:187], v[206:209], v[98:101]
	v_mfma_f32_16x16x32_bf16 v[86:89], v[174:177], v[214:217], v[86:89]
	s_setprio 2
	s_barrier
	v_mfma_f32_16x16x32_bf16 v[82:85], v[184:187], v[214:217], v[82:85]
	v_mfma_f32_16x16x32_bf16 v[70:73], v[174:177], v[222:225], v[70:73]
	v_mfma_f32_16x16x32_bf16 v[66:69], v[184:187], v[222:225], v[66:69]
	s_setprio 0
	s_add_i32 s70, s56, s3
	v_lshl_add_u64 v[226:227], s[44:45], 0, v[132:133]
	s_mov_b32 m0, s70
	ds_read_b128 v[188:191], v155 offset:16384
	ds_read_b128 v[198:201], v155 offset:17408
	ds_read_b128 v[202:205], v155 offset:18432
	ds_read_b128 v[206:209], v155 offset:19456
	ds_read_b128 v[210:213], v155 offset:20480
	ds_read_b128 v[214:217], v155 offset:21504
	ds_read_b128 v[218:221], v155 offset:22528
	ds_read_b128 v[222:225], v155 offset:23552
	global_load_lds_dwordx4 v[226:227], off
	s_add_i32 m0, s70, 0x2000
	s_add_u32 s70, s44, 0x4000
	v_lshl_add_u64 v[226:227], s[44:45], 0, v[136:137]
	s_addc_u32 s71, s45, 0
	s_add_i32 s72, s57, s3
	global_load_lds_dwordx4 v[226:227], off
	v_lshl_add_u64 v[226:227], s[70:71], 0, v[132:133]
	s_mov_b32 m0, s72
	s_nop 0
	global_load_lds_dwordx4 v[226:227], off
	v_lshl_add_u64 v[226:227], s[70:71], 0, v[136:137]
	s_add_i32 m0, s72, 0x2000
	s_nop 0
	global_load_lds_dwordx4 v[226:227], off
	s_waitcnt vmcnt(6)
	s_waitcnt lgkmcnt(0)
	s_barrier
; #define PG8_STAGE(bufoff, gbase, voff) do { _Pragma("unroll") for (int _i = 0; _i < 2; ++_i) \
;         __builtin_amdgcn_global_load_lds((const unsigned*)((const char*)(gbase) + (voff)[_i]), (PG8_LAS unsigned*)(lds + (bufoff) + ldsw + _i * 8192), 16, 0, 0); } while (0)
; #define PG8_LDA(dst, b, h) do { _Pragma("unroll") for (int m = 0; m < 4; ++m) _Pragma("unroll") for (int k = 0; k < 2; ++k) dst[m][k] = *(const PG8_LAS bf16x8*)(lds + PG8_SA(b, h) + aoff + m * 2048 + k * 1024); } while (0)
; #define PG8_LDB(dst, b, h) do { _Pragma("unroll") for (int n = 0; n < 2; ++n) _Pragma("unroll") for (int k = 0; k < 2; ++k) dst[n][k] = *(const PG8_LAS bf16x8*)(lds + PG8_SB(b, h) + boff + n * 2048 + k * 1024); } while (0)
; #define PG8_MMA(ai, bj, At, Bt) do { __builtin_amdgcn_s_setprio(1); _Pragma("unroll") for (int m = 0; m < 4; ++m) _Pragma("unroll") for (int n = 0; n < 2; ++n) _Pragma("unroll") for (int k = 0; k < 2; ++k) \
;         acc[ai][bj][m][n] = __builtin_amdgcn_mfma_f32_16x16x32_bf16(Bt[n][k], At[m][k], acc[ai][bj][m][n], 0, 0, 0); __builtin_amdgcn_s_setprio(0); } while (0)
; #define PG8_WAIT_V(n) asm volatile("s_waitcnt vmcnt(" #n ")" ::: "memory")
; #define PG8_WAIT_L(n) asm volatile("s_waitcnt lgkmcnt(" #n ")" ::: "memory")
; #define PG8_BAR __builtin_amdgcn_s_barrier()
; #define PG8_SCHED __builtin_amdgcn_sched_barrier(0)
; template <class Epi, class Sched, bool ALIGN_EPI = false, bool SP2 = false>
; __device__ __forceinline__ void gemm_phase(PG8_LAS unsigned char* lds, const Gemm g, const Sched& S, const Epi& E) {
;     ...
;             PG8_WAIT_V(8); PG8_WAIT_L(0); PG8_BAR; PG8_MMA(1, 0, At, B0); PG8_MMA(1, 1, At, B1); PG8_BAR; PG8_SCHED;
;             PG8_LDB(B0, 1, 0); PG8_LDB(B1, 1, 1); PG8_SCHED; PG8_LDA(At, 1, 0); PG8_STAGE(PG8_SA(0, 1), a2 + hstep, voffA);
;             PG8_WAIT_V(8); PG8_WAIT_L(0); PG8_BAR; PG8_MMA(0, 0, At, B0); PG8_MMA(0, 1, At, B1); PG8_BAR; PG8_SCHED;
;             PG8_LDA(At, 1, 1); PG8_STAGE(PG8_SB(1, 0), b3, voffB); PG8_STAGE(PG8_SB(1, 1), b3 + hstep, voffB); PG8_STAGE(PG8_SA(1, 0), a3, voffA);
;             PG8_WAIT_V(8); PG8_WAIT_L(0); PG8_BAR; PG8_MMA(1, 0, At, B0); PG8_MMA(1, 1, At, B1); PG8_BAR; PG8_SCHED;
	s_setprio 1
	s_waitcnt lgkmcnt(0)
	v_mfma_f32_16x16x32_bf16 v[62:65], v[148:151], v[188:191], v[62:65]
	v_mfma_f32_16x16x32_bf16 v[58:61], v[162:165], v[188:191], v[58:61]
	v_mfma_f32_16x16x32_bf16 v[46:49], v[148:151], v[202:205], v[46:49]
	v_mfma_f32_16x16x32_bf16 v[42:45], v[162:165], v[202:205], v[42:45]
	v_mfma_f32_16x16x32_bf16 v[30:33], v[148:151], v[210:213], v[30:33]
	v_mfma_f32_16x16x32_bf16 v[26:29], v[162:165], v[210:213], v[26:29]
	v_mfma_f32_16x16x32_bf16 v[14:17], v[148:151], v[218:221], v[14:17]
	v_mfma_f32_16x16x32_bf16 v[10:13], v[162:165], v[218:221], v[10:13]
	v_mfma_f32_16x16x32_bf16 v[62:65], v[158:161], v[198:201], v[62:65]
	v_mfma_f32_16x16x32_bf16 v[58:61], v[166:169], v[198:201], v[58:61]
	v_mfma_f32_16x16x32_bf16 v[46:49], v[158:161], v[206:209], v[46:49]
	v_mfma_f32_16x16x32_bf16 v[42:45], v[166:169], v[206:209], v[42:45]
	v_mfma_f32_16x16x32_bf16 v[30:33], v[158:161], v[214:217], v[30:33]
	v_mfma_f32_16x16x32_bf16 v[26:29], v[166:169], v[214:217], v[26:29]
	v_mfma_f32_16x16x32_bf16 v[14:17], v[158:161], v[222:225], v[14:17]
	v_mfma_f32_16x16x32_bf16 v[10:13], v[166:169], v[222:225], v[10:13]
	s_setprio 0
	s_setprio 1
	v_mfma_f32_16x16x32_bf16 v[54:57], v[170:173], v[188:191], v[54:57]
	v_mfma_f32_16x16x32_bf16 v[50:53], v[180:183], v[188:191], v[50:53]
	v_mfma_f32_16x16x32_bf16 v[38:41], v[170:173], v[202:205], v[38:41]
	v_mfma_f32_16x16x32_bf16 v[34:37], v[180:183], v[202:205], v[34:37]
	v_mfma_f32_16x16x32_bf16 v[22:25], v[170:173], v[210:213], v[22:25]
	v_mfma_f32_16x16x32_bf16 v[18:21], v[180:183], v[210:213], v[18:21]
	v_mfma_f32_16x16x32_bf16 v[6:9], v[170:173], v[218:221], v[6:9]
	v_mfma_f32_16x16x32_bf16 v[2:5], v[180:183], v[218:221], v[2:5]
	v_mfma_f32_16x16x32_bf16 v[54:57], v[174:177], v[198:201], v[54:57]
	v_mfma_f32_16x16x32_bf16 v[50:53], v[184:187], v[198:201], v[50:53]
	v_mfma_f32_16x16x32_bf16 v[38:41], v[174:177], v[206:209], v[38:41]
	v_mfma_f32_16x16x32_bf16 v[34:37], v[184:187], v[206:209], v[34:37]
	v_mfma_f32_16x16x32_bf16 v[22:25], v[174:177], v[214:217], v[22:25]
	s_setprio 2
	s_barrier
	v_mfma_f32_16x16x32_bf16 v[18:21], v[184:187], v[214:217], v[18:21]
	v_mfma_f32_16x16x32_bf16 v[6:9], v[174:177], v[222:225], v[6:9]
	v_mfma_f32_16x16x32_bf16 v[2:5], v[184:187], v[222:225], v[2:5]
	s_setprio 0
	s_add_i32 s70, 0, 0x18000
	v_add_u32_e32 v138, s70, v1
	s_add_i32 s71, 0, 0x1c000
	ds_read_b128 v[148:151], v138
	ds_read_b128 v[158:161], v138 offset:1024
	ds_read_b128 v[162:165], v138 offset:2048
	ds_read_b128 v[166:169], v138 offset:3072
	v_add_u32_e32 v138, s71, v1
	ds_read_b128 v[170:173], v138
	ds_read_b128 v[174:177], v138 offset:1024
	ds_read_b128 v[180:183], v138 offset:2048
	ds_read_b128 v[184:187], v138 offset:3072
	v_lshl_add_u64 v[226:227], s[46:47], 0, v[130:131]
	s_mov_b32 m0, s28
	s_nop 0
	global_load_lds_dwordx4 v[226:227], off
	v_lshl_add_u64 v[226:227], s[46:47], 0, v[134:135]
	s_mov_b32 m0, s29
	s_nop 0
	global_load_lds_dwordx4 v[226:227], off
	s_add_u32 s46, s46, 0x4000
	s_addc_u32 s47, s47, 0
	s_mov_b32 m0, s30
	v_lshl_add_u64 v[226:227], s[46:47], 0, v[130:131]
	ds_read_b128 v[188:191], v155 offset:32768
	ds_read_b128 v[198:201], v155 offset:33792
	ds_read_b128 v[202:205], v155 offset:34816
	ds_read_b128 v[206:209], v155 offset:35840
	ds_read_b128 v[210:213], v155 offset:36864
	ds_read_b128 v[214:217], v155 offset:37888
	ds_read_b128 v[218:221], v155 offset:38912
	ds_read_b128 v[222:225], v155 offset:39936
	global_load_lds_dwordx4 v[226:227], off
	v_lshl_add_u64 v[226:227], s[46:47], 0, v[134:135]
	s_mov_b32 m0, s31
	s_nop 0
	global_load_lds_dwordx4 v[226:227], off
	s_waitcnt vmcnt(8)
	s_waitcnt lgkmcnt(0)
	s_barrier
	s_setprio 1
	s_waitcnt lgkmcnt(0)
	v_mfma_f32_16x16x32_bf16 v[126:129], v[148:151], v[188:191], v[126:129]
	v_mfma_f32_16x16x32_bf16 v[122:125], v[162:165], v[188:191], v[122:125]
	v_mfma_f32_16x16x32_bf16 v[110:113], v[148:151], v[202:205], v[110:113]
	v_mfma_f32_16x16x32_bf16 v[106:109], v[162:165], v[202:205], v[106:109]
	v_mfma_f32_16x16x32_bf16 v[94:97], v[148:151], v[210:213], v[94:97]
	v_mfma_f32_16x16x32_bf16 v[90:93], v[162:165], v[210:213], v[90:93]
	v_mfma_f32_16x16x32_bf16 v[78:81], v[148:151], v[218:221], v[78:81]
	v_mfma_f32_16x16x32_bf16 v[74:77], v[162:165], v[218:221], v[74:77]
	v_mfma_f32_16x16x32_bf16 v[126:129], v[158:161], v[198:201], v[126:129]
	v_mfma_f32_16x16x32_bf16 v[122:125], v[166:169], v[198:201], v[122:125]
	v_mfma_f32_16x16x32_bf16 v[110:113], v[158:161], v[206:209], v[110:113]
	v_mfma_f32_16x16x32_bf16 v[106:109], v[166:169], v[206:209], v[106:109]
	v_mfma_f32_16x16x32_bf16 v[94:97], v[158:161], v[214:217], v[94:97]
	v_mfma_f32_16x16x32_bf16 v[90:93], v[166:169], v[214:217], v[90:93]
	v_mfma_f32_16x16x32_bf16 v[78:81], v[158:161], v[222:225], v[78:81]
	v_mfma_f32_16x16x32_bf16 v[74:77], v[166:169], v[222:225], v[74:77]
	s_setprio 0
	s_setprio 1
	v_mfma_f32_16x16x32_bf16 v[118:121], v[170:173], v[188:191], v[118:121]
	v_mfma_f32_16x16x32_bf16 v[114:117], v[180:183], v[188:191], v[114:117]
	v_mfma_f32_16x16x32_bf16 v[102:105], v[170:173], v[202:205], v[102:105]
	v_mfma_f32_16x16x32_bf16 v[98:101], v[180:183], v[202:205], v[98:101]
	v_mfma_f32_16x16x32_bf16 v[86:89], v[170:173], v[210:213], v[86:89]
	v_mfma_f32_16x16x32_bf16 v[82:85], v[180:183], v[210:213], v[82:85]
	v_mfma_f32_16x16x32_bf16 v[70:73], v[170:173], v[218:221], v[70:73]
	v_mfma_f32_16x16x32_bf16 v[66:69], v[180:183], v[218:221], v[66:69]
	v_mfma_f32_16x16x32_bf16 v[118:121], v[174:177], v[198:201], v[118:121]
	v_mfma_f32_16x16x32_bf16 v[114:117], v[184:187], v[198:201], v[114:117]
	v_mfma_f32_16x16x32_bf16 v[102:105], v[174:177], v[206:209], v[102:105]
	v_mfma_f32_16x16x32_bf16 v[98:101], v[184:187], v[206:209], v[98:101]
	v_mfma_f32_16x16x32_bf16 v[86:89], v[174:177], v[214:217], v[86:89]
	s_setprio 2
	s_barrier
; #define PG8_STAGE(bufoff, gbase, voff) do { _Pragma("unroll") for (int _i = 0; _i < 2; ++_i) \
;         __builtin_amdgcn_global_load_lds((const unsigned*)((const char*)(gbase) + (voff)[_i]), (PG8_LAS unsigned*)(lds + (bufoff) + ldsw + _i * 8192), 16, 0, 0); } while (0)
; #define PG8_LDA(dst, b, h) do { _Pragma("unroll") for (int m = 0; m < 4; ++m) _Pragma("unroll") for (int k = 0; k < 2; ++k) dst[m][k] = *(const PG8_LAS bf16x8*)(lds + PG8_SA(b, h) + aoff + m * 2048 + k * 1024); } while (0)
; #define PG8_MMA(ai, bj, At, Bt) do { __builtin_amdgcn_s_setprio(1); _Pragma("unroll") for (int m = 0; m < 4; ++m) _Pragma("unroll") for (int n = 0; n < 2; ++n) _Pragma("unroll") for (int k = 0; k < 2; ++k) \
;         acc[ai][bj][m][n] = __builtin_amdgcn_mfma_f32_16x16x32_bf16(Bt[n][k], At[m][k], acc[ai][bj][m][n], 0, 0, 0); __builtin_amdgcn_s_setprio(0); } while (0)
; #define PG8_WAIT_V(n) asm volatile("s_waitcnt vmcnt(" #n ")" ::: "memory")
; #define PG8_WAIT_L(n) asm volatile("s_waitcnt lgkmcnt(" #n ")" ::: "memory")
; #define PG8_BAR __builtin_amdgcn_s_barrier()
; #define PG8_SCHED __builtin_amdgcn_sched_barrier(0)
; template <class Epi, class Sched, bool ALIGN_EPI = false, bool SP2 = false>
; __device__ __forceinline__ void gemm_phase(PG8_LAS unsigned char* lds, const Gemm g, const Sched& S, const Epi& E) {
;     ...
;             PG8_WAIT_V(8); PG8_WAIT_L(0); PG8_BAR; PG8_MMA(0, 0, At, B0); PG8_MMA(0, 1, At, B1); PG8_BAR; PG8_SCHED;
;             PG8_LDA(At, 1, 1); PG8_STAGE(PG8_SB(1, 0), b3, voffB); PG8_STAGE(PG8_SB(1, 1), b3 + hstep, voffB); PG8_STAGE(PG8_SA(1, 0), a3, voffA);
;             PG8_WAIT_V(8); PG8_WAIT_L(0); PG8_BAR; PG8_MMA(1, 0, At, B0); PG8_MMA(1, 1, At, B1); PG8_BAR; PG8_SCHED;
;     ...
;         if constexpr (ALIGN_EPI) { if (wr == 0) PG8_BAR; }
	v_mfma_f32_16x16x32_bf16 v[82:85], v[184:187], v[214:217], v[82:85]
	v_mfma_f32_16x16x32_bf16 v[70:73], v[174:177], v[222:225], v[70:73]
	v_mfma_f32_16x16x32_bf16 v[66:69], v[184:187], v[222:225], v[66:69]
	s_setprio 0
	s_add_u32 s46, s44, 0x8000
	s_addc_u32 s47, s45, 0
	s_add_i32 s70, s70, s3
	v_lshl_add_u64 v[226:227], s[46:47], 0, v[132:133]
	s_mov_b32 m0, s70
	ds_read_b128 v[188:191], v155 offset:49152
	ds_read_b128 v[198:201], v155 offset:50176
	ds_read_b128 v[202:205], v155 offset:51200
	ds_read_b128 v[206:209], v155 offset:52224
	ds_read_b128 v[210:213], v155 offset:53248
	ds_read_b128 v[214:217], v155 offset:54272
	ds_read_b128 v[218:221], v155 offset:55296
	ds_read_b128 v[222:225], v155 offset:56320
	global_load_lds_dwordx4 v[226:227], off
	s_add_i32 m0, s70, 0x2000
	s_add_u32 s44, s44, 0xc000
	v_lshl_add_u64 v[226:227], s[46:47], 0, v[136:137]
	s_addc_u32 s45, s45, 0
	s_add_i32 s46, s71, s3
	global_load_lds_dwordx4 v[226:227], off
	v_lshl_add_u64 v[226:227], s[44:45], 0, v[132:133]
	s_mov_b32 m0, s46
	s_nop 0
	global_load_lds_dwordx4 v[226:227], off
	v_lshl_add_u64 v[226:227], s[44:45], 0, v[136:137]
	s_add_i32 m0, s46, 0x2000
	s_nop 0
	global_load_lds_dwordx4 v[226:227], off
	s_waitcnt vmcnt(6)
	s_waitcnt lgkmcnt(0)
	s_barrier
	s_setprio 1
	s_waitcnt lgkmcnt(0)
	v_mfma_f32_16x16x32_bf16 v[62:65], v[148:151], v[188:191], v[62:65]
	v_mfma_f32_16x16x32_bf16 v[58:61], v[162:165], v[188:191], v[58:61]
	v_mfma_f32_16x16x32_bf16 v[46:49], v[148:151], v[202:205], v[46:49]
	v_mfma_f32_16x16x32_bf16 v[42:45], v[162:165], v[202:205], v[42:45]
	v_mfma_f32_16x16x32_bf16 v[30:33], v[148:151], v[210:213], v[30:33]
	v_mfma_f32_16x16x32_bf16 v[26:29], v[162:165], v[210:213], v[26:29]
	v_mfma_f32_16x16x32_bf16 v[14:17], v[148:151], v[218:221], v[14:17]
	v_mfma_f32_16x16x32_bf16 v[10:13], v[162:165], v[218:221], v[10:13]
	v_mfma_f32_16x16x32_bf16 v[62:65], v[158:161], v[198:201], v[62:65]
	v_mfma_f32_16x16x32_bf16 v[58:61], v[166:169], v[198:201], v[58:61]
	v_mfma_f32_16x16x32_bf16 v[46:49], v[158:161], v[206:209], v[46:49]
	v_mfma_f32_16x16x32_bf16 v[42:45], v[166:169], v[206:209], v[42:45]
	v_mfma_f32_16x16x32_bf16 v[30:33], v[158:161], v[214:217], v[30:33]
	v_mfma_f32_16x16x32_bf16 v[26:29], v[166:169], v[214:217], v[26:29]
	v_mfma_f32_16x16x32_bf16 v[14:17], v[158:161], v[222:225], v[14:17]
	v_mfma_f32_16x16x32_bf16 v[10:13], v[166:169], v[222:225], v[10:13]
	s_setprio 0
	s_setprio 1
	v_mfma_f32_16x16x32_bf16 v[54:57], v[170:173], v[188:191], v[54:57]
	v_mfma_f32_16x16x32_bf16 v[50:53], v[180:183], v[188:191], v[50:53]
	v_mfma_f32_16x16x32_bf16 v[38:41], v[170:173], v[202:205], v[38:41]
	v_mfma_f32_16x16x32_bf16 v[34:37], v[180:183], v[202:205], v[34:37]
	v_mfma_f32_16x16x32_bf16 v[22:25], v[170:173], v[210:213], v[22:25]
	v_mfma_f32_16x16x32_bf16 v[18:21], v[180:183], v[210:213], v[18:21]
	v_mfma_f32_16x16x32_bf16 v[6:9], v[170:173], v[218:221], v[6:9]
	v_mfma_f32_16x16x32_bf16 v[2:5], v[180:183], v[218:221], v[2:5]
	v_mfma_f32_16x16x32_bf16 v[54:57], v[174:177], v[198:201], v[54:57]
	v_mfma_f32_16x16x32_bf16 v[50:53], v[184:187], v[198:201], v[50:53]
	v_mfma_f32_16x16x32_bf16 v[38:41], v[174:177], v[206:209], v[38:41]
	v_mfma_f32_16x16x32_bf16 v[34:37], v[184:187], v[206:209], v[34:37]
	v_mfma_f32_16x16x32_bf16 v[22:25], v[174:177], v[214:217], v[22:25]
	s_setprio 2
	s_barrier
	v_mfma_f32_16x16x32_bf16 v[18:21], v[184:187], v[214:217], v[18:21]
	v_mfma_f32_16x16x32_bf16 v[6:9], v[174:177], v[222:225], v[6:9]
	v_mfma_f32_16x16x32_bf16 v[2:5], v[184:187], v[222:225], v[2:5]
	s_setprio 0
	s_add_i32 s69, s69, 2
	s_add_u32 s40, s40, 0x10000
	s_addc_u32 s41, s41, 0
	s_add_u32 s67, s67, 0x10000
	s_addc_u32 s68, s68, 0
	s_cmp_gt_u32 s69, 61
	s_cbranch_scc0 .LBB0_840
	s_and_b64 vcc, exec, s[14:15]
	s_cbranch_vccz .LBB0_843
	s_barrier

; #define PG8_STAGE(bufoff, gbase, voff) do { _Pragma("unroll") for (int _i = 0; _i < 2; ++_i) \
;         __builtin_amdgcn_global_load_lds((const unsigned*)((const char*)(gbase) + (voff)[_i]), (PG8_LAS unsigned*)(lds + (bufoff) + ldsw + _i * 8192), 16, 0, 0); } while (0)
; #define PG8_LDA(dst, b, h) do { _Pragma("unroll") for (int m = 0; m < 4; ++m) _Pragma("unroll") for (int k = 0; k < 2; ++k) dst[m][k] = *(const PG8_LAS bf16x8*)(lds + PG8_SA(b, h) + aoff + m * 2048 + k * 1024); } while (0)
; #define PG8_LDB(dst, b, h) do { _Pragma("unroll") for (int n = 0; n < 2; ++n) _Pragma("unroll") for (int k = 0; k < 2; ++k) dst[n][k] = *(const PG8_LAS bf16x8*)(lds + PG8_SB(b, h) + boff + n * 2048 + k * 1024); } while (0)
; #define PG8_MMA(ai, bj, At, Bt) do { __builtin_amdgcn_s_setprio(1); _Pragma("unroll") for (int m = 0; m < 4; ++m) _Pragma("unroll") for (int n = 0; n < 2; ++n) _Pragma("unroll") for (int k = 0; k < 2; ++k) \
;         acc[ai][bj][m][n] = __builtin_amdgcn_mfma_f32_16x16x32_bf16(Bt[n][k], At[m][k], acc[ai][bj][m][n], 0, 0, 0); __builtin_amdgcn_s_setprio(0); } while (0)
; #define PG8_WAIT_V(n) asm volatile("s_waitcnt vmcnt(" #n ")" ::: "memory")
; #define PG8_WAIT_L(n) asm volatile("s_waitcnt lgkmcnt(" #n ")" ::: "memory")
; template <class Epi, class Sched, bool ALIGN_EPI = false, bool SP2 = false>
; __device__ __forceinline__ void gemm_phase(PG8_LAS unsigned char* lds, const Gemm g, const Sched& S, const Epi& E) {
;     ...
;         for (; t < tend; t += 2) {
;             const bool last = (t == nt - 2);
;             const char* a1 = cA + (size_t)(t + 1) * kstep;
;             const char* a2 = last ? nA : cA + (size_t)(t + 2) * kstep; const char* b2 = last ? nB : cB + (size_t)(t + 2) * kstep;
;             const char* a3 = a2 + kstep; const char* b3 = b2 + kstep;
;             if (last && has_next) S.a_ready(nxt);
;             if constexpr (SP2) {
;             PG8_LDB(B0, 0, 0); PG8_LDB(B1, 0, 1); PG8_SCHED; PG8_LDA(At, 0, 0); PG8_STAGE(PG8_SA(1, 1), a1 + hstep, voffA);
;             PG8_WAIT_V(8); PG8_WAIT_L(0); PG8_BAR; PG8_MMA(0, 0, At, B0); PG8_MMA(0, 1, At, B1); PG8_BAR; PG8_SCHED;
;             PG8_LDA(At, 0, 1); PG8_STAGE(PG8_SB(0, 0), b2, voffB); PG8_STAGE(PG8_SB(0, 1), b2 + hstep, voffB); PG8_STAGE(PG8_SA(0, 0), a2, voffA);
;             PG8_WAIT_V(8); PG8_WAIT_L(0); PG8_BAR; PG8_MMA(1, 0, At, B0); PG8_MMA(1, 1, At, B1); PG8_BAR; PG8_SCHED;
.LBB0_939:
	s_or_b32 s24, s59, 1
	s_lshl_b64 s[62:63], s[24:25], 15
	s_add_i32 s24, s59, 2
	ds_read_b128 v[156:159], v193
	ds_read_b128 v[160:163], v193 offset:1024
	ds_read_b128 v[196:199], v193 offset:2048
	ds_read_b128 v[200:203], v193 offset:3072
	ds_read_b128 v[204:207], v194
	ds_read_b128 v[208:211], v194 offset:1024
	ds_read_b128 v[212:215], v194 offset:2048
	ds_read_b128 v[216:219], v194 offset:3072
	s_lshl_b64 s[8:9], s[24:25], 15
	s_add_u32 s44, s6, s8
	s_addc_u32 s45, s7, s9
	s_cmpk_eq_i32 s59, 0xaa
	s_cselect_b32 s46, s58, s44
	s_cselect_b32 s47, s56, s45
	s_cselect_b32 s44, 0, s8
	s_cselect_b32 s45, 0, s9
	s_add_u32 s8, s46, 0x8000
	s_addc_u32 s9, s47, 0
	s_add_u32 s44, s14, s44
	s_addc_u32 s45, s15, s45
	s_add_u32 s62, s6, s62
	s_addc_u32 s63, s7, s63
	s_add_u32 s62, s62, 0x4000
	s_addc_u32 s63, s63, 0
	s_sub_u32 s8, s62, 0x4000
	s_subb_u32 s9, s63, 0
	v_lshl_add_u64 v[164:165], s[8:9], 0, v[130:131]
	s_mov_b32 m0, s51
	s_nop 0
	global_load_lds_dwordx4 v[164:165], off
	v_lshl_add_u64 v[164:165], s[8:9], 0, v[134:135]
	s_mov_b32 m0, s57
	s_nop 0
	global_load_lds_dwordx4 v[164:165], off
	v_lshl_add_u64 v[164:165], s[62:63], 0, v[130:131]
	s_add_i32 m0, s30, 0xc000
	ds_read_b128 v[220:223], v186
	ds_read_b128 v[224:227], v186 offset:1024
	ds_read_b128 v[228:231], v186 offset:2048
	ds_read_b128 v[232:235], v186 offset:3072
	ds_read_b128 v[236:239], v186 offset:4096
	ds_read_b128 v[240:243], v186 offset:5120
	ds_read_b128 v[244:247], v186 offset:6144
	ds_read_b128 v[248:251], v186 offset:7168
	global_load_lds_dwordx4 v[164:165], off
	v_lshl_add_u64 v[164:165], s[62:63], 0, v[134:135]
	s_add_i32 m0, s30, 0xe000
	s_nop 0
	global_load_lds_dwordx4 v[164:165], off
	s_waitcnt vmcnt(8)
	s_waitcnt lgkmcnt(0)
	s_barrier
	s_setprio 1
	s_waitcnt lgkmcnt(0)
	v_mfma_f32_16x16x32_bf16 v[126:129], v[156:159], v[220:223], v[126:129]
	v_mfma_f32_16x16x32_bf16 v[122:125], v[196:199], v[220:223], v[122:125]
	v_mfma_f32_16x16x32_bf16 v[110:113], v[156:159], v[228:231], v[110:113]
	v_mfma_f32_16x16x32_bf16 v[106:109], v[196:199], v[228:231], v[106:109]
	v_mfma_f32_16x16x32_bf16 v[94:97], v[156:159], v[236:239], v[94:97]
	v_mfma_f32_16x16x32_bf16 v[90:93], v[196:199], v[236:239], v[90:93]
	v_mfma_f32_16x16x32_bf16 v[78:81], v[156:159], v[244:247], v[78:81]
	v_mfma_f32_16x16x32_bf16 v[74:77], v[196:199], v[244:247], v[74:77]
	v_mfma_f32_16x16x32_bf16 v[126:129], v[160:163], v[224:227], v[126:129]
	v_mfma_f32_16x16x32_bf16 v[122:125], v[200:203], v[224:227], v[122:125]
	v_mfma_f32_16x16x32_bf16 v[110:113], v[160:163], v[232:235], v[110:113]
	v_mfma_f32_16x16x32_bf16 v[106:109], v[200:203], v[232:235], v[106:109]
	v_mfma_f32_16x16x32_bf16 v[94:97], v[160:163], v[240:243], v[94:97]
	v_mfma_f32_16x16x32_bf16 v[90:93], v[200:203], v[240:243], v[90:93]
	v_mfma_f32_16x16x32_bf16 v[78:81], v[160:163], v[248:251], v[78:81]
	v_mfma_f32_16x16x32_bf16 v[74:77], v[200:203], v[248:251], v[74:77]
	s_setprio 0
	s_setprio 1
	v_mfma_f32_16x16x32_bf16 v[118:121], v[204:207], v[220:223], v[118:121]
	v_mfma_f32_16x16x32_bf16 v[114:117], v[212:215], v[220:223], v[114:117]
	v_mfma_f32_16x16x32_bf16 v[102:105], v[204:207], v[228:231], v[102:105]
	v_mfma_f32_16x16x32_bf16 v[98:101], v[212:215], v[228:231], v[98:101]
	v_mfma_f32_16x16x32_bf16 v[86:89], v[204:207], v[236:239], v[86:89]
	v_mfma_f32_16x16x32_bf16 v[82:85], v[212:215], v[236:239], v[82:85]
	v_mfma_f32_16x16x32_bf16 v[70:73], v[204:207], v[244:247], v[70:73]
	v_mfma_f32_16x16x32_bf16 v[66:69], v[212:215], v[244:247], v[66:69]
	v_mfma_f32_16x16x32_bf16 v[118:121], v[208:211], v[224:227], v[118:121]
	v_mfma_f32_16x16x32_bf16 v[114:117], v[216:219], v[224:227], v[114:117]
	v_mfma_f32_16x16x32_bf16 v[102:105], v[208:211], v[232:235], v[102:105]
	v_mfma_f32_16x16x32_bf16 v[98:101], v[216:219], v[232:235], v[98:101]
	v_mfma_f32_16x16x32_bf16 v[86:89], v[208:211], v[240:243], v[86:89]
	s_setprio 2
	s_barrier
	v_mfma_f32_16x16x32_bf16 v[82:85], v[216:219], v[240:243], v[82:85]
	v_mfma_f32_16x16x32_bf16 v[70:73], v[208:211], v[248:251], v[70:73]
	v_mfma_f32_16x16x32_bf16 v[66:69], v[216:219], v[248:251], v[66:69]
	s_setprio 0
	s_add_i32 s62, s67, s29
	v_lshl_add_u64 v[164:165], s[44:45], 0, v[132:133]
	s_mov_b32 m0, s62
	ds_read_b128 v[220:223], v186 offset:16384
	ds_read_b128 v[224:227], v186 offset:17408
	ds_read_b128 v[228:231], v186 offset:18432
	ds_read_b128 v[232:235], v186 offset:19456
	ds_read_b128 v[236:239], v186 offset:20480
	ds_read_b128 v[240:243], v186 offset:21504
	ds_read_b128 v[244:247], v186 offset:22528
	ds_read_b128 v[248:251], v186 offset:23552
	global_load_lds_dwordx4 v[164:165], off
	s_add_i32 m0, s62, 0x2000
	s_add_u32 s62, s44, 0x4000
	v_lshl_add_u64 v[164:165], s[44:45], 0, v[136:137]
	s_addc_u32 s63, s45, 0
	s_add_i32 s72, s68, s29
	global_load_lds_dwordx4 v[164:165], off
	v_lshl_add_u64 v[164:165], s[62:63], 0, v[132:133]
	s_mov_b32 m0, s72
	s_nop 0
	global_load_lds_dwordx4 v[164:165], off
	v_lshl_add_u64 v[164:165], s[62:63], 0, v[136:137]
	s_add_i32 m0, s72, 0x2000
	s_nop 0
	global_load_lds_dwordx4 v[164:165], off
	s_waitcnt vmcnt(6)
	s_waitcnt lgkmcnt(0)
	s_barrier
; #define PG8_STAGE(bufoff, gbase, voff) do { _Pragma("unroll") for (int _i = 0; _i < 2; ++_i) \
;         __builtin_amdgcn_global_load_lds((const unsigned*)((const char*)(gbase) + (voff)[_i]), (PG8_LAS unsigned*)(lds + (bufoff) + ldsw + _i * 8192), 16, 0, 0); } while (0)
; #define PG8_LDA(dst, b, h) do { _Pragma("unroll") for (int m = 0; m < 4; ++m) _Pragma("unroll") for (int k = 0; k < 2; ++k) dst[m][k] = *(const PG8_LAS bf16x8*)(lds + PG8_SA(b, h) + aoff + m * 2048 + k * 1024); } while (0)
; #define PG8_LDB(dst, b, h) do { _Pragma("unroll") for (int n = 0; n < 2; ++n) _Pragma("unroll") for (int k = 0; k < 2; ++k) dst[n][k] = *(const PG8_LAS bf16x8*)(lds + PG8_SB(b, h) + boff + n * 2048 + k * 1024); } while (0)
; #define PG8_MMA(ai, bj, At, Bt) do { __builtin_amdgcn_s_setprio(1); _Pragma("unroll") for (int m = 0; m < 4; ++m) _Pragma("unroll") for (int n = 0; n < 2; ++n) _Pragma("unroll") for (int k = 0; k < 2; ++k) \
;         acc[ai][bj][m][n] = __builtin_amdgcn_mfma_f32_16x16x32_bf16(Bt[n][k], At[m][k], acc[ai][bj][m][n], 0, 0, 0); __builtin_amdgcn_s_setprio(0); } while (0)
; #define PG8_WAIT_V(n) asm volatile("s_waitcnt vmcnt(" #n ")" ::: "memory")
; #define PG8_WAIT_L(n) asm volatile("s_waitcnt lgkmcnt(" #n ")" ::: "memory")
; #define PG8_BAR __builtin_amdgcn_s_barrier()
; #define PG8_SCHED __builtin_amdgcn_sched_barrier(0)
; template <class Epi, class Sched, bool ALIGN_EPI = false, bool SP2 = false>
; __device__ __forceinline__ void gemm_phase(PG8_LAS unsigned char* lds, const Gemm g, const Sched& S, const Epi& E) {
;     ...
;             PG8_WAIT_V(8); PG8_WAIT_L(0); PG8_BAR; PG8_MMA(1, 0, At, B0); PG8_MMA(1, 1, At, B1); PG8_BAR; PG8_SCHED;
;             PG8_LDB(B0, 1, 0); PG8_LDB(B1, 1, 1); PG8_SCHED; PG8_LDA(At, 1, 0); PG8_STAGE(PG8_SA(0, 1), a2 + hstep, voffA);
;             PG8_WAIT_V(8); PG8_WAIT_L(0); PG8_BAR; PG8_MMA(0, 0, At, B0); PG8_MMA(0, 1, At, B1); PG8_BAR; PG8_SCHED;
;             PG8_LDA(At, 1, 1); PG8_STAGE(PG8_SB(1, 0), b3, voffB); PG8_STAGE(PG8_SB(1, 1), b3 + hstep, voffB); PG8_STAGE(PG8_SA(1, 0), a3, voffA);
;             PG8_WAIT_V(8); PG8_WAIT_L(0); PG8_BAR; PG8_MMA(1, 0, At, B0); PG8_MMA(1, 1, At, B1); PG8_BAR; PG8_SCHED;
	s_setprio 1
	s_waitcnt lgkmcnt(0)
	v_mfma_f32_16x16x32_bf16 v[62:65], v[156:159], v[220:223], v[62:65]
	v_mfma_f32_16x16x32_bf16 v[58:61], v[196:199], v[220:223], v[58:61]
	v_mfma_f32_16x16x32_bf16 v[46:49], v[156:159], v[228:231], v[46:49]
	v_mfma_f32_16x16x32_bf16 v[42:45], v[196:199], v[228:231], v[42:45]
	v_mfma_f32_16x16x32_bf16 v[30:33], v[156:159], v[236:239], v[30:33]
	v_mfma_f32_16x16x32_bf16 v[26:29], v[196:199], v[236:239], v[26:29]
	v_mfma_f32_16x16x32_bf16 v[14:17], v[156:159], v[244:247], v[14:17]
	v_mfma_f32_16x16x32_bf16 v[10:13], v[196:199], v[244:247], v[10:13]
	v_mfma_f32_16x16x32_bf16 v[62:65], v[160:163], v[224:227], v[62:65]
	v_mfma_f32_16x16x32_bf16 v[58:61], v[200:203], v[224:227], v[58:61]
	v_mfma_f32_16x16x32_bf16 v[46:49], v[160:163], v[232:235], v[46:49]
	v_mfma_f32_16x16x32_bf16 v[42:45], v[200:203], v[232:235], v[42:45]
	v_mfma_f32_16x16x32_bf16 v[30:33], v[160:163], v[240:243], v[30:33]
	v_mfma_f32_16x16x32_bf16 v[26:29], v[200:203], v[240:243], v[26:29]
	v_mfma_f32_16x16x32_bf16 v[14:17], v[160:163], v[248:251], v[14:17]
	v_mfma_f32_16x16x32_bf16 v[10:13], v[200:203], v[248:251], v[10:13]
	s_setprio 0
	s_setprio 1
	v_mfma_f32_16x16x32_bf16 v[54:57], v[204:207], v[220:223], v[54:57]
	v_mfma_f32_16x16x32_bf16 v[50:53], v[212:215], v[220:223], v[50:53]
	v_mfma_f32_16x16x32_bf16 v[38:41], v[204:207], v[228:231], v[38:41]
	v_mfma_f32_16x16x32_bf16 v[34:37], v[212:215], v[228:231], v[34:37]
	v_mfma_f32_16x16x32_bf16 v[22:25], v[204:207], v[236:239], v[22:25]
	v_mfma_f32_16x16x32_bf16 v[18:21], v[212:215], v[236:239], v[18:21]
	v_mfma_f32_16x16x32_bf16 v[6:9], v[204:207], v[244:247], v[6:9]
	v_mfma_f32_16x16x32_bf16 v[2:5], v[212:215], v[244:247], v[2:5]
	v_mfma_f32_16x16x32_bf16 v[54:57], v[208:211], v[224:227], v[54:57]
	v_mfma_f32_16x16x32_bf16 v[50:53], v[216:219], v[224:227], v[50:53]
	v_mfma_f32_16x16x32_bf16 v[38:41], v[208:211], v[232:235], v[38:41]
	v_mfma_f32_16x16x32_bf16 v[34:37], v[216:219], v[232:235], v[34:37]
	v_mfma_f32_16x16x32_bf16 v[22:25], v[208:211], v[240:243], v[22:25]
	s_setprio 2
	s_barrier
	v_mfma_f32_16x16x32_bf16 v[18:21], v[216:219], v[240:243], v[18:21]
	v_mfma_f32_16x16x32_bf16 v[6:9], v[208:211], v[248:251], v[6:9]
	v_mfma_f32_16x16x32_bf16 v[2:5], v[216:219], v[248:251], v[2:5]
	s_setprio 0
	s_add_i32 s62, 0, 0x18000
	v_add_u32_e32 v145, s62, v166
	s_add_i32 s63, 0, 0x1c000
	ds_read_b128 v[156:159], v145
	ds_read_b128 v[160:163], v145 offset:1024
	ds_read_b128 v[196:199], v145 offset:2048
	ds_read_b128 v[200:203], v145 offset:3072
	v_add_u32_e32 v145, s63, v166
	ds_read_b128 v[204:207], v145
	ds_read_b128 v[208:211], v145 offset:1024
	ds_read_b128 v[212:215], v145 offset:2048
	ds_read_b128 v[216:219], v145 offset:3072
	v_lshl_add_u64 v[164:165], s[46:47], 0, v[130:131]
	s_mov_b32 m0, s30
	s_nop 0
	global_load_lds_dwordx4 v[164:165], off
	v_lshl_add_u64 v[164:165], s[46:47], 0, v[134:135]
	s_mov_b32 m0, s31
	s_nop 0
	global_load_lds_dwordx4 v[164:165], off
	s_add_u32 s46, s46, 0x4000
	s_addc_u32 s47, s47, 0
	s_mov_b32 m0, s35
	v_lshl_add_u64 v[164:165], s[46:47], 0, v[130:131]
	ds_read_b128 v[220:223], v186 offset:32768
	ds_read_b128 v[224:227], v186 offset:33792
	ds_read_b128 v[228:231], v186 offset:34816
	ds_read_b128 v[232:235], v186 offset:35840
	ds_read_b128 v[236:239], v186 offset:36864
	ds_read_b128 v[240:243], v186 offset:37888
	ds_read_b128 v[244:247], v186 offset:38912
	ds_read_b128 v[248:251], v186 offset:39936
	global_load_lds_dwordx4 v[164:165], off
	v_lshl_add_u64 v[164:165], s[46:47], 0, v[134:135]
	s_mov_b32 m0, s48
	s_nop 0
	global_load_lds_dwordx4 v[164:165], off
	s_waitcnt vmcnt(8)
	s_waitcnt lgkmcnt(0)
	s_barrier
	s_setprio 1
	s_waitcnt lgkmcnt(0)
	v_mfma_f32_16x16x32_bf16 v[126:129], v[156:159], v[220:223], v[126:129]
	v_mfma_f32_16x16x32_bf16 v[122:125], v[196:199], v[220:223], v[122:125]
	v_mfma_f32_16x16x32_bf16 v[110:113], v[156:159], v[228:231], v[110:113]
	v_mfma_f32_16x16x32_bf16 v[106:109], v[196:199], v[228:231], v[106:109]
	v_mfma_f32_16x16x32_bf16 v[94:97], v[156:159], v[236:239], v[94:97]
	v_mfma_f32_16x16x32_bf16 v[90:93], v[196:199], v[236:239], v[90:93]
	v_mfma_f32_16x16x32_bf16 v[78:81], v[156:159], v[244:247], v[78:81]
	v_mfma_f32_16x16x32_bf16 v[74:77], v[196:199], v[244:247], v[74:77]
	v_mfma_f32_16x16x32_bf16 v[126:129], v[160:163], v[224:227], v[126:129]
	v_mfma_f32_16x16x32_bf16 v[122:125], v[200:203], v[224:227], v[122:125]
	v_mfma_f32_16x16x32_bf16 v[110:113], v[160:163], v[232:235], v[110:113]
	v_mfma_f32_16x16x32_bf16 v[106:109], v[200:203], v[232:235], v[106:109]
	v_mfma_f32_16x16x32_bf16 v[94:97], v[160:163], v[240:243], v[94:97]
	v_mfma_f32_16x16x32_bf16 v[90:93], v[200:203], v[240:243], v[90:93]
	v_mfma_f32_16x16x32_bf16 v[78:81], v[160:163], v[248:251], v[78:81]
	v_mfma_f32_16x16x32_bf16 v[74:77], v[200:203], v[248:251], v[74:77]
	s_setprio 0
	s_setprio 1
	v_mfma_f32_16x16x32_bf16 v[118:121], v[204:207], v[220:223], v[118:121]
	v_mfma_f32_16x16x32_bf16 v[114:117], v[212:215], v[220:223], v[114:117]
	v_mfma_f32_16x16x32_bf16 v[102:105], v[204:207], v[228:231], v[102:105]
	v_mfma_f32_16x16x32_bf16 v[98:101], v[212:215], v[228:231], v[98:101]
	v_mfma_f32_16x16x32_bf16 v[86:89], v[204:207], v[236:239], v[86:89]
	v_mfma_f32_16x16x32_bf16 v[82:85], v[212:215], v[236:239], v[82:85]
	v_mfma_f32_16x16x32_bf16 v[70:73], v[204:207], v[244:247], v[70:73]
	v_mfma_f32_16x16x32_bf16 v[66:69], v[212:215], v[244:247], v[66:69]
	v_mfma_f32_16x16x32_bf16 v[118:121], v[208:211], v[224:227], v[118:121]
	v_mfma_f32_16x16x32_bf16 v[114:117], v[216:219], v[224:227], v[114:117]
	v_mfma_f32_16x16x32_bf16 v[102:105], v[208:211], v[232:235], v[102:105]
	v_mfma_f32_16x16x32_bf16 v[98:101], v[216:219], v[232:235], v[98:101]
	v_mfma_f32_16x16x32_bf16 v[86:89], v[208:211], v[240:243], v[86:89]
	s_setprio 2
	s_barrier
; #define PG8_STAGE(bufoff, gbase, voff) do { _Pragma("unroll") for (int _i = 0; _i < 2; ++_i) \
;         __builtin_amdgcn_global_load_lds((const unsigned*)((const char*)(gbase) + (voff)[_i]), (PG8_LAS unsigned*)(lds + (bufoff) + ldsw + _i * 8192), 16, 0, 0); } while (0)
; #define PG8_LDA(dst, b, h) do { _Pragma("unroll") for (int m = 0; m < 4; ++m) _Pragma("unroll") for (int k = 0; k < 2; ++k) dst[m][k] = *(const PG8_LAS bf16x8*)(lds + PG8_SA(b, h) + aoff + m * 2048 + k * 1024); } while (0)
; #define PG8_MMA(ai, bj, At, Bt) do { __builtin_amdgcn_s_setprio(1); _Pragma("unroll") for (int m = 0; m < 4; ++m) _Pragma("unroll") for (int n = 0; n < 2; ++n) _Pragma("unroll") for (int k = 0; k < 2; ++k) \
;         acc[ai][bj][m][n] = __builtin_amdgcn_mfma_f32_16x16x32_bf16(Bt[n][k], At[m][k], acc[ai][bj][m][n], 0, 0, 0); __builtin_amdgcn_s_setprio(0); } while (0)
; #define PG8_WAIT_V(n) asm volatile("s_waitcnt vmcnt(" #n ")" ::: "memory")
; #define PG8_WAIT_L(n) asm volatile("s_waitcnt lgkmcnt(" #n ")" ::: "memory")
; #define PG8_BAR __builtin_amdgcn_s_barrier()
; #define PG8_SCHED __builtin_amdgcn_sched_barrier(0)
; template <class Epi, class Sched, bool ALIGN_EPI = false, bool SP2 = false>
; __device__ __forceinline__ void gemm_phase(PG8_LAS unsigned char* lds, const Gemm g, const Sched& S, const Epi& E) {
;     ...
;             PG8_WAIT_V(8); PG8_WAIT_L(0); PG8_BAR; PG8_MMA(0, 0, At, B0); PG8_MMA(0, 1, At, B1); PG8_BAR; PG8_SCHED;
;             PG8_LDA(At, 1, 1); PG8_STAGE(PG8_SB(1, 0), b3, voffB); PG8_STAGE(PG8_SB(1, 1), b3 + hstep, voffB); PG8_STAGE(PG8_SA(1, 0), a3, voffA);
;             PG8_WAIT_V(8); PG8_WAIT_L(0); PG8_BAR; PG8_MMA(1, 0, At, B0); PG8_MMA(1, 1, At, B1); PG8_BAR; PG8_SCHED;
;     ...
;         if constexpr (ALIGN_EPI) { if (wr == 0) PG8_BAR; }
	v_mfma_f32_16x16x32_bf16 v[82:85], v[216:219], v[240:243], v[82:85]
	v_mfma_f32_16x16x32_bf16 v[70:73], v[208:211], v[248:251], v[70:73]
	v_mfma_f32_16x16x32_bf16 v[66:69], v[216:219], v[248:251], v[66:69]
	s_setprio 0
	s_add_u32 s46, s44, 0x8000
	s_addc_u32 s47, s45, 0
	s_add_i32 s62, s62, s29
	v_lshl_add_u64 v[164:165], s[46:47], 0, v[132:133]
	s_mov_b32 m0, s62
	ds_read_b128 v[220:223], v186 offset:49152
	ds_read_b128 v[224:227], v186 offset:50176
	ds_read_b128 v[228:231], v186 offset:51200
	ds_read_b128 v[232:235], v186 offset:52224
	ds_read_b128 v[236:239], v186 offset:53248
	ds_read_b128 v[240:243], v186 offset:54272
	ds_read_b128 v[244:247], v186 offset:55296
	ds_read_b128 v[248:251], v186 offset:56320
	global_load_lds_dwordx4 v[164:165], off
	s_add_i32 m0, s62, 0x2000
	s_add_u32 s44, s44, 0xc000
	v_lshl_add_u64 v[164:165], s[46:47], 0, v[136:137]
	s_addc_u32 s45, s45, 0
	s_add_i32 s46, s63, s29
	global_load_lds_dwordx4 v[164:165], off
	v_lshl_add_u64 v[164:165], s[44:45], 0, v[132:133]
	s_mov_b32 m0, s46
	s_nop 0
	global_load_lds_dwordx4 v[164:165], off
	v_lshl_add_u64 v[164:165], s[44:45], 0, v[136:137]
	s_add_i32 m0, s46, 0x2000
	s_nop 0
	global_load_lds_dwordx4 v[164:165], off
	s_waitcnt vmcnt(6)
	s_waitcnt lgkmcnt(0)
	s_barrier
	s_setprio 1
	s_waitcnt lgkmcnt(0)
	v_mfma_f32_16x16x32_bf16 v[62:65], v[156:159], v[220:223], v[62:65]
	v_mfma_f32_16x16x32_bf16 v[58:61], v[196:199], v[220:223], v[58:61]
	v_mfma_f32_16x16x32_bf16 v[46:49], v[156:159], v[228:231], v[46:49]
	v_mfma_f32_16x16x32_bf16 v[42:45], v[196:199], v[228:231], v[42:45]
	v_mfma_f32_16x16x32_bf16 v[30:33], v[156:159], v[236:239], v[30:33]
	v_mfma_f32_16x16x32_bf16 v[26:29], v[196:199], v[236:239], v[26:29]
	v_mfma_f32_16x16x32_bf16 v[14:17], v[156:159], v[244:247], v[14:17]
	v_mfma_f32_16x16x32_bf16 v[10:13], v[196:199], v[244:247], v[10:13]
	v_mfma_f32_16x16x32_bf16 v[62:65], v[160:163], v[224:227], v[62:65]
	v_mfma_f32_16x16x32_bf16 v[58:61], v[200:203], v[224:227], v[58:61]
	v_mfma_f32_16x16x32_bf16 v[46:49], v[160:163], v[232:235], v[46:49]
	v_mfma_f32_16x16x32_bf16 v[42:45], v[200:203], v[232:235], v[42:45]
	v_mfma_f32_16x16x32_bf16 v[30:33], v[160:163], v[240:243], v[30:33]
	v_mfma_f32_16x16x32_bf16 v[26:29], v[200:203], v[240:243], v[26:29]
	v_mfma_f32_16x16x32_bf16 v[14:17], v[160:163], v[248:251], v[14:17]
	v_mfma_f32_16x16x32_bf16 v[10:13], v[200:203], v[248:251], v[10:13]
	s_setprio 0
	s_setprio 1
	v_mfma_f32_16x16x32_bf16 v[54:57], v[204:207], v[220:223], v[54:57]
	v_mfma_f32_16x16x32_bf16 v[50:53], v[212:215], v[220:223], v[50:53]
	v_mfma_f32_16x16x32_bf16 v[38:41], v[204:207], v[228:231], v[38:41]
	v_mfma_f32_16x16x32_bf16 v[34:37], v[212:215], v[228:231], v[34:37]
	v_mfma_f32_16x16x32_bf16 v[22:25], v[204:207], v[236:239], v[22:25]
	v_mfma_f32_16x16x32_bf16 v[18:21], v[212:215], v[236:239], v[18:21]
	v_mfma_f32_16x16x32_bf16 v[6:9], v[204:207], v[244:247], v[6:9]
	v_mfma_f32_16x16x32_bf16 v[2:5], v[212:215], v[244:247], v[2:5]
	v_mfma_f32_16x16x32_bf16 v[54:57], v[208:211], v[224:227], v[54:57]
	v_mfma_f32_16x16x32_bf16 v[50:53], v[216:219], v[224:227], v[50:53]
	v_mfma_f32_16x16x32_bf16 v[38:41], v[208:211], v[232:235], v[38:41]
	v_mfma_f32_16x16x32_bf16 v[34:37], v[216:219], v[232:235], v[34:37]
	v_mfma_f32_16x16x32_bf16 v[22:25], v[208:211], v[240:243], v[22:25]
	s_setprio 2
	s_barrier
	v_mfma_f32_16x16x32_bf16 v[18:21], v[216:219], v[240:243], v[18:21]
	v_mfma_f32_16x16x32_bf16 v[6:9], v[208:211], v[248:251], v[6:9]
	v_mfma_f32_16x16x32_bf16 v[2:5], v[216:219], v[248:251], v[2:5]
	s_setprio 0
	s_cmpk_gt_u32 s59, 0xa9
	s_mov_b32 s59, s24
	s_cbranch_scc0 .LBB0_939
	s_and_b64 vcc, exec, s[38:39]
	s_cbranch_vccz .LBB0_942
	s_barrier
